# K-loop s_setprio toggles removed (loader wave no longer starved of issue slots behind the MFMA wave), on top of SGPR-base DMA addressing + lean in-proj epilogue
# speedup vs baseline: 1.0141x; 1.0039x over previous
; #define PG8_STAGE(bufoff, gbase, voff) do { _Pragma("unroll") for (int _i = 0; _i < 2; ++_i) \
;         __builtin_amdgcn_global_load_lds((const unsigned*)((const char*)(gbase) + (voff)[_i]), (PG8_LAS unsigned*)(lds + (bufoff) + ldsw + _i * 8192), 16, 0, 0); } while (0)
; #define PG8_LDA(dst, b, h) do { _Pragma("unroll") for (int m = 0; m < 4; ++m) _Pragma("unroll") for (int k = 0; k < 2; ++k) dst[m][k] = *(const PG8_LAS bf16x8*)(lds + PG8_SA(b, h) + aoff + m * 2048 + k * 1024); } while (0)
; #define PG8_LDB(dst, b, h) do { _Pragma("unroll") for (int n = 0; n < 2; ++n) _Pragma("unroll") for (int k = 0; k < 2; ++k) dst[n][k] = *(const PG8_LAS bf16x8*)(lds + PG8_SB(b, h) + boff + n * 2048 + k * 1024); } while (0)
; #define PG8_MMA(ai, bj, At, Bt) do { __builtin_amdgcn_s_setprio(1); _Pragma("unroll") for (int m = 0; m < 4; ++m) _Pragma("unroll") for (int n = 0; n < 2; ++n) _Pragma("unroll") for (int k = 0; k < 2; ++k) \
;         acc[ai][bj][m][n] = __builtin_amdgcn_mfma_f32_16x16x32_bf16(Bt[n][k], At[m][k], acc[ai][bj][m][n], 0, 0, 0); __builtin_amdgcn_s_setprio(0); } while (0)
; #define PG8_WAIT_V(n) asm volatile("s_waitcnt vmcnt(" #n ")" ::: "memory")
; #define PG8_WAIT_L(n) asm volatile("s_waitcnt lgkmcnt(" #n ")" ::: "memory")
; template <class Epi, class Sched, bool ALIGN_EPI = false, bool SP2 = false>
; __device__ __forceinline__ void gemm_phase(PG8_LAS unsigned char* lds, const Gemm g, const Sched& S, const Epi& E) {
;     ...
;             const bool last = (t == nt - 2);
;             const char* a1 = cA + (size_t)(t + 1) * kstep;
;             const char* a2 = last ? nA : cA + (size_t)(t + 2) * kstep; const char* b2 = last ? nB : cB + (size_t)(t + 2) * kstep;
;             const char* a3 = a2 + kstep; const char* b3 = b2 + kstep;
;             if (last && has_next) S.a_ready(nxt);
;             if constexpr (SP2) {
;             PG8_LDB(B0, 0, 0); PG8_LDB(B1, 0, 1); PG8_SCHED; PG8_LDA(At, 0, 0); PG8_STAGE(PG8_SA(1, 1), a1 + hstepA, voffA);
;             PG8_WAIT_V(8); PG8_WAIT_L(0); PG8_BAR; PG8_MMA(0, 0, At, B0); PG8_MMA(0, 1, At, B1); PG8_BAR; PG8_SCHED;
;             PG8_LDA(At, 0, 1); PG8_STAGE(PG8_SB(0, 0), b2, voffB); PG8_STAGE(PG8_SB(0, 1), b2 + hstepB, voffB); PG8_STAGE(PG8_SA(0, 0), a2, voffA);
;             PG8_WAIT_V(8); PG8_WAIT_L(0); PG8_BAR; PG8_MMA(1, 0, At, B0); PG8_MMA(1, 1, At, B1); PG8_BAR; PG8_SCHED;
.LBB0_634:
	s_add_u32 s2, s0, 0xfffc0080
	s_addc_u32 s3, s1, -1
	s_add_i32 s30, 0, 0x10000
	s_cmp_eq_u32 s95, 12
	s_cselect_b32 s85, s17, s3
	s_cselect_b32 s84, s78, s2
	s_cselect_b32 s7, s15, s94
	s_cselect_b32 s6, s87, s93
	s_add_i32 s31, 0, 0x14000
	v_add_u32_e32 v140, s30, v230
	v_add_u32_e32 v156, s31, v230
	ds_read_b128 v[112:115], v140
	ds_read_b128 v[120:123], v140 offset:1024
	ds_read_b128 v[128:131], v140 offset:2048
	ds_read_b128 v[140:143], v140 offset:3072
	ds_read_b128 v[144:147], v156
	ds_read_b128 v[148:151], v156 offset:1024
	ds_read_b128 v[152:155], v156 offset:2048
	ds_read_b128 v[156:159], v156 offset:3072
	s_add_i32 m0, s20, 0xc000
	ds_read_b128 v[160:163], v231
	ds_read_b128 v[164:167], v231 offset:1024
	ds_read_b128 v[168:171], v231 offset:2048
	ds_read_b128 v[172:175], v231 offset:3072
	ds_read_b128 v[186:189], v231 offset:4096
	ds_read_b128 v[198:201], v231 offset:5120
	ds_read_b128 v[202:205], v231 offset:6144
	ds_read_b128 v[206:209], v231 offset:7168
	global_load_lds_dwordx4 v184, s[0:1]
	s_add_i32 m0, s20, 0xe000
	s_nop 0
	global_load_lds_dwordx4 v182, s[0:1]
	s_waitcnt vmcnt(8)
	s_waitcnt lgkmcnt(0)
	s_barrier
	s_waitcnt lgkmcnt(0)
	v_mfma_f32_16x16x32_bf16 v[136:139], v[112:115], v[160:163], v[136:139]
	v_mfma_f32_16x16x32_bf16 v[132:135], v[128:131], v[160:163], v[132:135]
	v_mfma_f32_16x16x32_bf16 v[108:111], v[112:115], v[168:171], v[108:111]
	v_mfma_f32_16x16x32_bf16 v[104:107], v[128:131], v[168:171], v[104:107]
	v_mfma_f32_16x16x32_bf16 v[92:95], v[112:115], v[186:189], v[92:95]
	v_mfma_f32_16x16x32_bf16 v[88:91], v[128:131], v[186:189], v[88:91]
	v_mfma_f32_16x16x32_bf16 v[76:79], v[112:115], v[202:205], v[76:79]
	v_mfma_f32_16x16x32_bf16 v[72:75], v[128:131], v[202:205], v[72:75]
	v_mfma_f32_16x16x32_bf16 v[136:139], v[120:123], v[164:167], v[136:139]
	v_mfma_f32_16x16x32_bf16 v[132:135], v[140:143], v[164:167], v[132:135]
	v_mfma_f32_16x16x32_bf16 v[108:111], v[120:123], v[172:175], v[108:111]
	v_mfma_f32_16x16x32_bf16 v[104:107], v[140:143], v[172:175], v[104:107]
	v_mfma_f32_16x16x32_bf16 v[92:95], v[120:123], v[198:201], v[92:95]
	v_mfma_f32_16x16x32_bf16 v[88:91], v[140:143], v[198:201], v[88:91]
	v_mfma_f32_16x16x32_bf16 v[76:79], v[120:123], v[206:209], v[76:79]
	v_mfma_f32_16x16x32_bf16 v[72:75], v[140:143], v[206:209], v[72:75]
	v_mfma_f32_16x16x32_bf16 v[124:127], v[144:147], v[160:163], v[124:127]
	v_mfma_f32_16x16x32_bf16 v[116:119], v[152:155], v[160:163], v[116:119]
	v_mfma_f32_16x16x32_bf16 v[100:103], v[144:147], v[168:171], v[100:103]
	v_mfma_f32_16x16x32_bf16 v[96:99], v[152:155], v[168:171], v[96:99]
	v_mfma_f32_16x16x32_bf16 v[84:87], v[144:147], v[186:189], v[84:87]
	v_mfma_f32_16x16x32_bf16 v[80:83], v[152:155], v[186:189], v[80:83]
	v_mfma_f32_16x16x32_bf16 v[68:71], v[144:147], v[202:205], v[68:71]
	v_mfma_f32_16x16x32_bf16 v[64:67], v[152:155], v[202:205], v[64:67]
	v_mfma_f32_16x16x32_bf16 v[124:127], v[148:151], v[164:167], v[124:127]
	v_mfma_f32_16x16x32_bf16 v[116:119], v[156:159], v[164:167], v[116:119]
	v_mfma_f32_16x16x32_bf16 v[100:103], v[148:151], v[172:175], v[100:103]
	v_mfma_f32_16x16x32_bf16 v[96:99], v[156:159], v[172:175], v[96:99]
	v_mfma_f32_16x16x32_bf16 v[84:87], v[148:151], v[198:201], v[84:87]
	v_mfma_f32_16x16x32_bf16 v[80:83], v[156:159], v[198:201], v[80:83]
	v_mfma_f32_16x16x32_bf16 v[68:71], v[148:151], v[206:209], v[68:71]
	v_mfma_f32_16x16x32_bf16 v[64:67], v[156:159], v[206:209], v[64:67]
	s_barrier
	s_add_i32 s2, s30, s19
	s_mov_b32 m0, s2
	ds_read_b128 v[160:163], v231 offset:16384
	ds_read_b128 v[164:167], v231 offset:17408
	ds_read_b128 v[168:171], v231 offset:18432
	ds_read_b128 v[172:175], v231 offset:19456
	ds_read_b128 v[186:189], v231 offset:20480
	ds_read_b128 v[198:201], v231 offset:21504
	ds_read_b128 v[202:205], v231 offset:22528
	ds_read_b128 v[206:209], v231 offset:23552
	global_load_lds_dwordx4 v192, s[6:7]
	s_add_i32 m0, s2, 0x2000
	s_add_u32 s2, s6, 0x40000
	s_addc_u32 s3, s7, 0
	s_add_i32 s30, s31, s19
	global_load_lds_dwordx4 v176, s[6:7]
	s_mov_b32 m0, s30
	s_nop 0
	global_load_lds_dwordx4 v192, s[2:3]
	s_add_i32 m0, s30, 0x2000
	s_nop 0
	global_load_lds_dwordx4 v176, s[2:3]
	s_mov_b32 m0, s20
	s_nop 0
	global_load_lds_dwordx4 v180, s[84:85]
	s_mov_b32 m0, s21
	s_nop 0
	global_load_lds_dwordx4 v178, s[84:85]
	s_waitcnt vmcnt(8)
	s_waitcnt lgkmcnt(0)
	s_barrier
	s_waitcnt lgkmcnt(0)
	v_mfma_f32_16x16x32_bf16 v[60:63], v[112:115], v[160:163], v[60:63]
	v_mfma_f32_16x16x32_bf16 v[56:59], v[128:131], v[160:163], v[56:59]
	v_mfma_f32_16x16x32_bf16 v[44:47], v[112:115], v[168:171], v[44:47]
	v_mfma_f32_16x16x32_bf16 v[40:43], v[128:131], v[168:171], v[40:43]
	v_mfma_f32_16x16x32_bf16 v[28:31], v[112:115], v[186:189], v[28:31]
	v_mfma_f32_16x16x32_bf16 v[24:27], v[128:131], v[186:189], v[24:27]
	v_mfma_f32_16x16x32_bf16 v[12:15], v[112:115], v[202:205], v[12:15]
	v_mfma_f32_16x16x32_bf16 v[8:11], v[128:131], v[202:205], v[8:11]
	v_mfma_f32_16x16x32_bf16 v[60:63], v[120:123], v[164:167], v[60:63]
	v_mfma_f32_16x16x32_bf16 v[56:59], v[140:143], v[164:167], v[56:59]
	v_mfma_f32_16x16x32_bf16 v[44:47], v[120:123], v[172:175], v[44:47]
	v_mfma_f32_16x16x32_bf16 v[40:43], v[140:143], v[172:175], v[40:43]
	v_mfma_f32_16x16x32_bf16 v[28:31], v[120:123], v[198:201], v[28:31]
	v_mfma_f32_16x16x32_bf16 v[24:27], v[140:143], v[198:201], v[24:27]
	v_mfma_f32_16x16x32_bf16 v[12:15], v[120:123], v[206:209], v[12:15]
	v_mfma_f32_16x16x32_bf16 v[8:11], v[140:143], v[206:209], v[8:11]
	v_mfma_f32_16x16x32_bf16 v[52:55], v[144:147], v[160:163], v[52:55]
	v_mfma_f32_16x16x32_bf16 v[48:51], v[152:155], v[160:163], v[48:51]
	v_mfma_f32_16x16x32_bf16 v[36:39], v[144:147], v[168:171], v[36:39]
	v_mfma_f32_16x16x32_bf16 v[32:35], v[152:155], v[168:171], v[32:35]
	v_mfma_f32_16x16x32_bf16 v[20:23], v[144:147], v[186:189], v[20:23]
	v_mfma_f32_16x16x32_bf16 v[16:19], v[152:155], v[186:189], v[16:19]
	v_mfma_f32_16x16x32_bf16 v[4:7], v[144:147], v[202:205], v[4:7]
	v_mfma_f32_16x16x32_bf16 v[0:3], v[152:155], v[202:205], v[0:3]
	v_mfma_f32_16x16x32_bf16 v[52:55], v[148:151], v[164:167], v[52:55]
	v_mfma_f32_16x16x32_bf16 v[48:51], v[156:159], v[164:167], v[48:51]
	v_mfma_f32_16x16x32_bf16 v[36:39], v[148:151], v[172:175], v[36:39]
	v_mfma_f32_16x16x32_bf16 v[32:35], v[156:159], v[172:175], v[32:35]
	v_mfma_f32_16x16x32_bf16 v[20:23], v[148:151], v[198:201], v[20:23]
	v_mfma_f32_16x16x32_bf16 v[16:19], v[156:159], v[198:201], v[16:19]
	v_mfma_f32_16x16x32_bf16 v[4:7], v[148:151], v[206:209], v[4:7]
	v_mfma_f32_16x16x32_bf16 v[0:3], v[156:159], v[206:209], v[0:3]
	s_barrier
; #define PG8_STAGE(bufoff, gbase, voff) do { _Pragma("unroll") for (int _i = 0; _i < 2; ++_i) \
;         __builtin_amdgcn_global_load_lds((const unsigned*)((const char*)(gbase) + (voff)[_i]), (PG8_LAS unsigned*)(lds + (bufoff) + ldsw + _i * 8192), 16, 0, 0); } while (0)
; #define PG8_LDA(dst, b, h) do { _Pragma("unroll") for (int m = 0; m < 4; ++m) _Pragma("unroll") for (int k = 0; k < 2; ++k) dst[m][k] = *(const PG8_LAS bf16x8*)(lds + PG8_SA(b, h) + aoff + m * 2048 + k * 1024); } while (0)
; #define PG8_LDB(dst, b, h) do { _Pragma("unroll") for (int n = 0; n < 2; ++n) _Pragma("unroll") for (int k = 0; k < 2; ++k) dst[n][k] = *(const PG8_LAS bf16x8*)(lds + PG8_SB(b, h) + boff + n * 2048 + k * 1024); } while (0)
; #define PG8_MMA(ai, bj, At, Bt) do { __builtin_amdgcn_s_setprio(1); _Pragma("unroll") for (int m = 0; m < 4; ++m) _Pragma("unroll") for (int n = 0; n < 2; ++n) _Pragma("unroll") for (int k = 0; k < 2; ++k) \
;         acc[ai][bj][m][n] = __builtin_amdgcn_mfma_f32_16x16x32_bf16(Bt[n][k], At[m][k], acc[ai][bj][m][n], 0, 0, 0); __builtin_amdgcn_s_setprio(0); } while (0)
; #define PG8_WAIT_V(n) asm volatile("s_waitcnt vmcnt(" #n ")" ::: "memory")
; #define PG8_WAIT_L(n) asm volatile("s_waitcnt lgkmcnt(" #n ")" ::: "memory")
; #define PG8_BAR __builtin_amdgcn_s_barrier()
; #define PG8_SCHED __builtin_amdgcn_sched_barrier(0)
; template <class Epi, class Sched, bool ALIGN_EPI = false, bool SP2 = false>
; __device__ __forceinline__ void gemm_phase(PG8_LAS unsigned char* lds, const Gemm g, const Sched& S, const Epi& E) {
;     ...
;             PG8_LDB(B0, 1, 0); PG8_LDB(B1, 1, 1); PG8_SCHED; PG8_LDA(At, 1, 0); PG8_STAGE(PG8_SA(0, 1), a2 + hstepA, voffA);
;             PG8_WAIT_V(8); PG8_WAIT_L(0); PG8_BAR; PG8_MMA(0, 0, At, B0); PG8_MMA(0, 1, At, B1); PG8_BAR; PG8_SCHED;
;             PG8_LDA(At, 1, 1); PG8_STAGE(PG8_SB(1, 0), b3, voffB); PG8_STAGE(PG8_SB(1, 1), b3 + hstepB, voffB); PG8_STAGE(PG8_SA(1, 0), a3, voffA);
;             PG8_WAIT_V(8); PG8_WAIT_L(0); PG8_BAR; PG8_MMA(1, 0, At, B0); PG8_MMA(1, 1, At, B1); PG8_BAR; PG8_SCHED;
	s_add_i32 s30, 0, 0x18000
	s_add_i32 s31, 0, 0x1c000
	v_add_u32_e32 v140, s30, v230
	v_add_u32_e32 v156, s31, v230
	ds_read_b128 v[112:115], v140
	ds_read_b128 v[120:123], v140 offset:1024
	ds_read_b128 v[128:131], v140 offset:2048
	ds_read_b128 v[140:143], v140 offset:3072
	ds_read_b128 v[144:147], v156
	ds_read_b128 v[148:151], v156 offset:1024
	ds_read_b128 v[152:155], v156 offset:2048
	ds_read_b128 v[156:159], v156 offset:3072
	s_add_u32 s2, s84, 0x40000
	s_addc_u32 s3, s85, 0
	s_mov_b32 m0, s45
	ds_read_b128 v[160:163], v231 offset:32768
	ds_read_b128 v[164:167], v231 offset:33792
	ds_read_b128 v[168:171], v231 offset:34816
	ds_read_b128 v[172:175], v231 offset:35840
	ds_read_b128 v[186:189], v231 offset:36864
	ds_read_b128 v[198:201], v231 offset:37888
	ds_read_b128 v[202:205], v231 offset:38912
	ds_read_b128 v[206:209], v231 offset:39936
	global_load_lds_dwordx4 v180, s[2:3]
	s_mov_b32 m0, s49
	s_nop 0
	global_load_lds_dwordx4 v178, s[2:3]
	s_waitcnt vmcnt(8)
	s_waitcnt lgkmcnt(0)
	s_barrier
	s_waitcnt lgkmcnt(0)
	v_mfma_f32_16x16x32_bf16 v[136:139], v[112:115], v[160:163], v[136:139]
	v_mfma_f32_16x16x32_bf16 v[132:135], v[128:131], v[160:163], v[132:135]
	v_mfma_f32_16x16x32_bf16 v[108:111], v[112:115], v[168:171], v[108:111]
	v_mfma_f32_16x16x32_bf16 v[104:107], v[128:131], v[168:171], v[104:107]
	v_mfma_f32_16x16x32_bf16 v[92:95], v[112:115], v[186:189], v[92:95]
	v_mfma_f32_16x16x32_bf16 v[88:91], v[128:131], v[186:189], v[88:91]
	v_mfma_f32_16x16x32_bf16 v[76:79], v[112:115], v[202:205], v[76:79]
	v_mfma_f32_16x16x32_bf16 v[72:75], v[128:131], v[202:205], v[72:75]
	v_mfma_f32_16x16x32_bf16 v[136:139], v[120:123], v[164:167], v[136:139]
	v_mfma_f32_16x16x32_bf16 v[132:135], v[140:143], v[164:167], v[132:135]
	v_mfma_f32_16x16x32_bf16 v[108:111], v[120:123], v[172:175], v[108:111]
	v_mfma_f32_16x16x32_bf16 v[104:107], v[140:143], v[172:175], v[104:107]
	v_mfma_f32_16x16x32_bf16 v[92:95], v[120:123], v[198:201], v[92:95]
	v_mfma_f32_16x16x32_bf16 v[88:91], v[140:143], v[198:201], v[88:91]
	v_mfma_f32_16x16x32_bf16 v[76:79], v[120:123], v[206:209], v[76:79]
	v_mfma_f32_16x16x32_bf16 v[72:75], v[140:143], v[206:209], v[72:75]
	v_mfma_f32_16x16x32_bf16 v[124:127], v[144:147], v[160:163], v[124:127]
	v_mfma_f32_16x16x32_bf16 v[116:119], v[152:155], v[160:163], v[116:119]
	v_mfma_f32_16x16x32_bf16 v[100:103], v[144:147], v[168:171], v[100:103]
	v_mfma_f32_16x16x32_bf16 v[96:99], v[152:155], v[168:171], v[96:99]
	v_mfma_f32_16x16x32_bf16 v[84:87], v[144:147], v[186:189], v[84:87]
	v_mfma_f32_16x16x32_bf16 v[80:83], v[152:155], v[186:189], v[80:83]
	v_mfma_f32_16x16x32_bf16 v[68:71], v[144:147], v[202:205], v[68:71]
	v_mfma_f32_16x16x32_bf16 v[64:67], v[152:155], v[202:205], v[64:67]
	v_mfma_f32_16x16x32_bf16 v[124:127], v[148:151], v[164:167], v[124:127]
	v_mfma_f32_16x16x32_bf16 v[116:119], v[156:159], v[164:167], v[116:119]
	v_mfma_f32_16x16x32_bf16 v[100:103], v[148:151], v[172:175], v[100:103]
	v_mfma_f32_16x16x32_bf16 v[96:99], v[156:159], v[172:175], v[96:99]
	v_mfma_f32_16x16x32_bf16 v[84:87], v[148:151], v[198:201], v[84:87]
	v_mfma_f32_16x16x32_bf16 v[80:83], v[156:159], v[198:201], v[80:83]
	v_mfma_f32_16x16x32_bf16 v[68:71], v[148:151], v[206:209], v[68:71]
	v_mfma_f32_16x16x32_bf16 v[64:67], v[156:159], v[206:209], v[64:67]
	s_barrier
	s_add_i32 s2, s30, s19
	s_add_i32 m0, s2, 0xffffff80
	ds_read_b128 v[160:163], v231 offset:49152
	ds_read_b128 v[164:167], v231 offset:50176
	ds_read_b128 v[168:171], v231 offset:51200
	ds_read_b128 v[172:175], v231 offset:52224
	ds_read_b128 v[186:189], v231 offset:53248
	ds_read_b128 v[198:201], v231 offset:54272
	ds_read_b128 v[202:205], v231 offset:55296
	ds_read_b128 v[206:209], v231 offset:56320
	global_load_lds_dwordx4 v192, s[6:7] offset:128
	s_add_i32 m0, s2, 0x1f80
	s_add_u32 s2, s6, 0x40080
	global_load_lds_dwordx4 v176, s[6:7] offset:128
	s_addc_u32 s3, s7, 0
	s_add_i32 s6, s31, s19
	s_mov_b32 m0, s6
	s_nop 0
	global_load_lds_dwordx4 v192, s[2:3]
	s_add_i32 m0, s6, 0x2000
	s_nop 0
	global_load_lds_dwordx4 v176, s[2:3]
	s_add_i32 m0, s65, 0xffffff80
	s_nop 0
	global_load_lds_dwordx4 v180, s[84:85] offset:128
	s_add_i32 m0, s80, 0xffffff80
	s_nop 0
	global_load_lds_dwordx4 v178, s[84:85] offset:128
	s_waitcnt vmcnt(8)
	s_waitcnt lgkmcnt(0)
	s_barrier
	s_waitcnt lgkmcnt(0)
	v_mfma_f32_16x16x32_bf16 v[60:63], v[112:115], v[160:163], v[60:63]
	v_mfma_f32_16x16x32_bf16 v[56:59], v[128:131], v[160:163], v[56:59]
	v_mfma_f32_16x16x32_bf16 v[44:47], v[112:115], v[168:171], v[44:47]
	v_mfma_f32_16x16x32_bf16 v[40:43], v[128:131], v[168:171], v[40:43]
	v_mfma_f32_16x16x32_bf16 v[28:31], v[112:115], v[186:189], v[28:31]
	v_mfma_f32_16x16x32_bf16 v[24:27], v[128:131], v[186:189], v[24:27]
	v_mfma_f32_16x16x32_bf16 v[12:15], v[112:115], v[202:205], v[12:15]
	v_mfma_f32_16x16x32_bf16 v[8:11], v[128:131], v[202:205], v[8:11]
	v_mfma_f32_16x16x32_bf16 v[60:63], v[120:123], v[164:167], v[60:63]
	v_mfma_f32_16x16x32_bf16 v[56:59], v[140:143], v[164:167], v[56:59]
	v_mfma_f32_16x16x32_bf16 v[44:47], v[120:123], v[172:175], v[44:47]
	v_mfma_f32_16x16x32_bf16 v[40:43], v[140:143], v[172:175], v[40:43]
	v_mfma_f32_16x16x32_bf16 v[28:31], v[120:123], v[198:201], v[28:31]
	v_mfma_f32_16x16x32_bf16 v[24:27], v[140:143], v[198:201], v[24:27]
	v_mfma_f32_16x16x32_bf16 v[12:15], v[120:123], v[206:209], v[12:15]
	v_mfma_f32_16x16x32_bf16 v[8:11], v[140:143], v[206:209], v[8:11]
	v_mfma_f32_16x16x32_bf16 v[52:55], v[144:147], v[160:163], v[52:55]
	v_mfma_f32_16x16x32_bf16 v[48:51], v[152:155], v[160:163], v[48:51]
	v_mfma_f32_16x16x32_bf16 v[36:39], v[144:147], v[168:171], v[36:39]
	v_mfma_f32_16x16x32_bf16 v[32:35], v[152:155], v[168:171], v[32:35]
	v_mfma_f32_16x16x32_bf16 v[20:23], v[144:147], v[186:189], v[20:23]
	v_mfma_f32_16x16x32_bf16 v[16:19], v[152:155], v[186:189], v[16:19]
	v_mfma_f32_16x16x32_bf16 v[4:7], v[144:147], v[202:205], v[4:7]
	v_mfma_f32_16x16x32_bf16 v[0:3], v[152:155], v[202:205], v[0:3]
	v_mfma_f32_16x16x32_bf16 v[52:55], v[148:151], v[164:167], v[52:55]
	v_mfma_f32_16x16x32_bf16 v[48:51], v[156:159], v[164:167], v[48:51]
	v_mfma_f32_16x16x32_bf16 v[36:39], v[148:151], v[172:175], v[36:39]
	v_mfma_f32_16x16x32_bf16 v[32:35], v[156:159], v[172:175], v[32:35]
	v_mfma_f32_16x16x32_bf16 v[20:23], v[148:151], v[198:201], v[20:23]
	v_mfma_f32_16x16x32_bf16 v[16:19], v[156:159], v[198:201], v[16:19]
	v_mfma_f32_16x16x32_bf16 v[4:7], v[148:151], v[206:209], v[4:7]
	v_mfma_f32_16x16x32_bf16 v[0:3], v[156:159], v[206:209], v[0:3]
	s_barrier
	s_add_i32 s95, s95, 2
	s_add_u32 s93, s93, 0x100
	s_addc_u32 s94, s94, 0
	s_add_u32 s0, s0, 0x100
	s_addc_u32 s1, s1, 0
	s_cmp_gt_u32 s95, 13
	s_cbranch_scc0 .LBB0_634
	s_and_b64 vcc, exec, s[12:13]
	s_cbranch_vccz .LBB0_637
	s_barrier

; #define PG8_STAGE(bufoff, gbase, voff) do { _Pragma("unroll") for (int _i = 0; _i < 2; ++_i) \
;         __builtin_amdgcn_global_load_lds((const unsigned*)((const char*)(gbase) + (voff)[_i]), (PG8_LAS unsigned*)(lds + (bufoff) + ldsw + _i * 8192), 16, 0, 0); } while (0)
; #define PG8_LDA(dst, b, h) do { _Pragma("unroll") for (int m = 0; m < 4; ++m) _Pragma("unroll") for (int k = 0; k < 2; ++k) dst[m][k] = *(const PG8_LAS bf16x8*)(lds + PG8_SA(b, h) + aoff + m * 2048 + k * 1024); } while (0)
; #define PG8_LDB(dst, b, h) do { _Pragma("unroll") for (int n = 0; n < 2; ++n) _Pragma("unroll") for (int k = 0; k < 2; ++k) dst[n][k] = *(const PG8_LAS bf16x8*)(lds + PG8_SB(b, h) + boff + n * 2048 + k * 1024); } while (0)
; #define PG8_MMA(ai, bj, At, Bt) do { __builtin_amdgcn_s_setprio(1); _Pragma("unroll") for (int m = 0; m < 4; ++m) _Pragma("unroll") for (int n = 0; n < 2; ++n) _Pragma("unroll") for (int k = 0; k < 2; ++k) \
;         acc[ai][bj][m][n] = __builtin_amdgcn_mfma_f32_16x16x32_bf16(Bt[n][k], At[m][k], acc[ai][bj][m][n], 0, 0, 0); __builtin_amdgcn_s_setprio(0); } while (0)
; #define PG8_WAIT_V(n) asm volatile("s_waitcnt vmcnt(" #n ")" ::: "memory")
; #define PG8_WAIT_L(n) asm volatile("s_waitcnt lgkmcnt(" #n ")" ::: "memory")
; template <class Epi, class Sched, bool ALIGN_EPI = false, bool SP2 = false>
; __device__ __forceinline__ void gemm_phase(PG8_LAS unsigned char* lds, const Gemm g, const Sched& S, const Epi& E) {
;     ...
;             const bool last = (t == nt - 2);
;             const char* a1 = cA + (size_t)(t + 1) * kstep;
;             const char* a2 = last ? nA : cA + (size_t)(t + 2) * kstep; const char* b2 = last ? nB : cB + (size_t)(t + 2) * kstep;
;             const char* a3 = a2 + kstep; const char* b3 = b2 + kstep;
;             if (last && has_next) S.a_ready(nxt);
;             if constexpr (SP2) {
;             PG8_LDB(B0, 0, 0); PG8_LDB(B1, 0, 1); PG8_SCHED; PG8_LDA(At, 0, 0); PG8_STAGE(PG8_SA(1, 1), a1 + hstepA, voffA);
;             PG8_WAIT_V(8); PG8_WAIT_L(0); PG8_BAR; PG8_MMA(0, 0, At, B0); PG8_MMA(0, 1, At, B1); PG8_BAR; PG8_SCHED;
;             PG8_LDA(At, 0, 1); PG8_STAGE(PG8_SB(0, 0), b2, voffB); PG8_STAGE(PG8_SB(0, 1), b2 + hstepB, voffB); PG8_STAGE(PG8_SA(0, 0), a2, voffA);
;             PG8_WAIT_V(8); PG8_WAIT_L(0); PG8_BAR; PG8_MMA(1, 0, At, B0); PG8_MMA(1, 1, At, B1); PG8_BAR; PG8_SCHED;
.LBB0_693:
	s_add_u32 s2, s4, 0xfffc0080
	s_addc_u32 s3, s5, -1
	s_add_i32 s30, 0, 0x10000
	s_cmp_eq_u32 s92, 12
	s_cselect_b32 s87, s17, s3
	s_cselect_b32 s86, s78, s2
	s_cselect_b32 s85, s15, s91
	s_cselect_b32 s84, s89, s90
	s_add_i32 s31, 0, 0x14000
	v_add_u32_e32 v140, s30, v182
	v_add_u32_e32 v166, s31, v182
	ds_read_b128 v[128:131], v140
	ds_read_b128 v[132:135], v140 offset:1024
	ds_read_b128 v[136:139], v140 offset:2048
	ds_read_b128 v[140:143], v140 offset:3072
	ds_read_b128 v[144:147], v166
	ds_read_b128 v[148:151], v166 offset:1024
	ds_read_b128 v[152:155], v166 offset:2048
	ds_read_b128 v[166:169], v166 offset:3072
	s_add_i32 m0, s20, 0xc000
	ds_read_b128 v[170:173], v183
	ds_read_b128 v[174:177], v183 offset:1024
	ds_read_b128 v[178:181], v183 offset:2048
	ds_read_b128 v[184:187], v183 offset:3072
	ds_read_b128 v[188:191], v183 offset:4096
	ds_read_b128 v[198:201], v183 offset:5120
	ds_read_b128 v[202:205], v183 offset:6144
	ds_read_b128 v[206:209], v183 offset:7168
	global_load_lds_dwordx4 v164, s[4:5]
	s_add_i32 m0, s20, 0xe000
	s_nop 0
	global_load_lds_dwordx4 v162, s[4:5]
	s_waitcnt vmcnt(8)
	s_waitcnt lgkmcnt(0)
	s_barrier
	s_waitcnt lgkmcnt(0)
	v_mfma_f32_16x16x32_bf16 v[124:127], v[128:131], v[170:173], v[124:127]
	v_mfma_f32_16x16x32_bf16 v[120:123], v[136:139], v[170:173], v[120:123]
	v_mfma_f32_16x16x32_bf16 v[108:111], v[128:131], v[178:181], v[108:111]
	v_mfma_f32_16x16x32_bf16 v[104:107], v[136:139], v[178:181], v[104:107]
	v_mfma_f32_16x16x32_bf16 v[92:95], v[128:131], v[188:191], v[92:95]
	v_mfma_f32_16x16x32_bf16 v[88:91], v[136:139], v[188:191], v[88:91]
	v_mfma_f32_16x16x32_bf16 v[76:79], v[128:131], v[202:205], v[76:79]
	v_mfma_f32_16x16x32_bf16 v[72:75], v[136:139], v[202:205], v[72:75]
	v_mfma_f32_16x16x32_bf16 v[124:127], v[132:135], v[174:177], v[124:127]
	v_mfma_f32_16x16x32_bf16 v[120:123], v[140:143], v[174:177], v[120:123]
	v_mfma_f32_16x16x32_bf16 v[108:111], v[132:135], v[184:187], v[108:111]
	v_mfma_f32_16x16x32_bf16 v[104:107], v[140:143], v[184:187], v[104:107]
	v_mfma_f32_16x16x32_bf16 v[92:95], v[132:135], v[198:201], v[92:95]
	v_mfma_f32_16x16x32_bf16 v[88:91], v[140:143], v[198:201], v[88:91]
	v_mfma_f32_16x16x32_bf16 v[76:79], v[132:135], v[206:209], v[76:79]
	v_mfma_f32_16x16x32_bf16 v[72:75], v[140:143], v[206:209], v[72:75]
	v_mfma_f32_16x16x32_bf16 v[116:119], v[144:147], v[170:173], v[116:119]
	v_mfma_f32_16x16x32_bf16 v[112:115], v[152:155], v[170:173], v[112:115]
	v_mfma_f32_16x16x32_bf16 v[100:103], v[144:147], v[178:181], v[100:103]
	v_mfma_f32_16x16x32_bf16 v[96:99], v[152:155], v[178:181], v[96:99]
	v_mfma_f32_16x16x32_bf16 v[84:87], v[144:147], v[188:191], v[84:87]
	v_mfma_f32_16x16x32_bf16 v[80:83], v[152:155], v[188:191], v[80:83]
	v_mfma_f32_16x16x32_bf16 v[68:71], v[144:147], v[202:205], v[68:71]
	v_mfma_f32_16x16x32_bf16 v[64:67], v[152:155], v[202:205], v[64:67]
	v_mfma_f32_16x16x32_bf16 v[116:119], v[148:151], v[174:177], v[116:119]
	v_mfma_f32_16x16x32_bf16 v[112:115], v[166:169], v[174:177], v[112:115]
	v_mfma_f32_16x16x32_bf16 v[100:103], v[148:151], v[184:187], v[100:103]
	v_mfma_f32_16x16x32_bf16 v[96:99], v[166:169], v[184:187], v[96:99]
	v_mfma_f32_16x16x32_bf16 v[84:87], v[148:151], v[198:201], v[84:87]
	v_mfma_f32_16x16x32_bf16 v[80:83], v[166:169], v[198:201], v[80:83]
	v_mfma_f32_16x16x32_bf16 v[68:71], v[148:151], v[206:209], v[68:71]
	v_mfma_f32_16x16x32_bf16 v[64:67], v[166:169], v[206:209], v[64:67]
	s_barrier
	s_add_i32 s2, s30, s19
	s_mov_b32 m0, s2
	ds_read_b128 v[170:173], v183 offset:16384
	ds_read_b128 v[174:177], v183 offset:17408
	ds_read_b128 v[178:181], v183 offset:18432
	ds_read_b128 v[184:187], v183 offset:19456
	ds_read_b128 v[188:191], v183 offset:20480
	ds_read_b128 v[198:201], v183 offset:21504
	ds_read_b128 v[202:205], v183 offset:22528
	ds_read_b128 v[206:209], v183 offset:23552
	global_load_lds_dwordx4 v192, s[84:85]
	s_add_i32 m0, s2, 0x2000
	s_add_u32 s2, s84, 0x40000
	s_addc_u32 s3, s85, 0
	s_add_i32 s30, s31, s19
	global_load_lds_dwordx4 v156, s[84:85]
	s_mov_b32 m0, s30
	s_nop 0
	global_load_lds_dwordx4 v192, s[2:3]
	s_add_i32 m0, s30, 0x2000
	s_nop 0
	global_load_lds_dwordx4 v156, s[2:3]
	s_mov_b32 m0, s20
	s_nop 0
	global_load_lds_dwordx4 v160, s[86:87]
	s_mov_b32 m0, s21
	s_nop 0
	global_load_lds_dwordx4 v158, s[86:87]
	s_waitcnt vmcnt(8)
	s_waitcnt lgkmcnt(0)
	s_barrier
	s_waitcnt lgkmcnt(0)
	v_mfma_f32_16x16x32_bf16 v[60:63], v[128:131], v[170:173], v[60:63]
	v_mfma_f32_16x16x32_bf16 v[56:59], v[136:139], v[170:173], v[56:59]
	v_mfma_f32_16x16x32_bf16 v[44:47], v[128:131], v[178:181], v[44:47]
	v_mfma_f32_16x16x32_bf16 v[40:43], v[136:139], v[178:181], v[40:43]
	v_mfma_f32_16x16x32_bf16 v[28:31], v[128:131], v[188:191], v[28:31]
	v_mfma_f32_16x16x32_bf16 v[24:27], v[136:139], v[188:191], v[24:27]
	v_mfma_f32_16x16x32_bf16 v[12:15], v[128:131], v[202:205], v[12:15]
	v_mfma_f32_16x16x32_bf16 v[8:11], v[136:139], v[202:205], v[8:11]
	v_mfma_f32_16x16x32_bf16 v[60:63], v[132:135], v[174:177], v[60:63]
	v_mfma_f32_16x16x32_bf16 v[56:59], v[140:143], v[174:177], v[56:59]
	v_mfma_f32_16x16x32_bf16 v[44:47], v[132:135], v[184:187], v[44:47]
	v_mfma_f32_16x16x32_bf16 v[40:43], v[140:143], v[184:187], v[40:43]
	v_mfma_f32_16x16x32_bf16 v[28:31], v[132:135], v[198:201], v[28:31]
	v_mfma_f32_16x16x32_bf16 v[24:27], v[140:143], v[198:201], v[24:27]
	v_mfma_f32_16x16x32_bf16 v[12:15], v[132:135], v[206:209], v[12:15]
	v_mfma_f32_16x16x32_bf16 v[8:11], v[140:143], v[206:209], v[8:11]
	v_mfma_f32_16x16x32_bf16 v[52:55], v[144:147], v[170:173], v[52:55]
	v_mfma_f32_16x16x32_bf16 v[48:51], v[152:155], v[170:173], v[48:51]
	v_mfma_f32_16x16x32_bf16 v[36:39], v[144:147], v[178:181], v[36:39]
	v_mfma_f32_16x16x32_bf16 v[32:35], v[152:155], v[178:181], v[32:35]
	v_mfma_f32_16x16x32_bf16 v[20:23], v[144:147], v[188:191], v[20:23]
	v_mfma_f32_16x16x32_bf16 v[16:19], v[152:155], v[188:191], v[16:19]
	v_mfma_f32_16x16x32_bf16 v[4:7], v[144:147], v[202:205], v[4:7]
	v_mfma_f32_16x16x32_bf16 v[0:3], v[152:155], v[202:205], v[0:3]
	v_mfma_f32_16x16x32_bf16 v[52:55], v[148:151], v[174:177], v[52:55]
	v_mfma_f32_16x16x32_bf16 v[48:51], v[166:169], v[174:177], v[48:51]
	v_mfma_f32_16x16x32_bf16 v[36:39], v[148:151], v[184:187], v[36:39]
	v_mfma_f32_16x16x32_bf16 v[32:35], v[166:169], v[184:187], v[32:35]
	v_mfma_f32_16x16x32_bf16 v[20:23], v[148:151], v[198:201], v[20:23]
	v_mfma_f32_16x16x32_bf16 v[16:19], v[166:169], v[198:201], v[16:19]
	v_mfma_f32_16x16x32_bf16 v[4:7], v[148:151], v[206:209], v[4:7]
	v_mfma_f32_16x16x32_bf16 v[0:3], v[166:169], v[206:209], v[0:3]
	s_barrier
; #define PG8_STAGE(bufoff, gbase, voff) do { _Pragma("unroll") for (int _i = 0; _i < 2; ++_i) \
;         __builtin_amdgcn_global_load_lds((const unsigned*)((const char*)(gbase) + (voff)[_i]), (PG8_LAS unsigned*)(lds + (bufoff) + ldsw + _i * 8192), 16, 0, 0); } while (0)
; #define PG8_LDA(dst, b, h) do { _Pragma("unroll") for (int m = 0; m < 4; ++m) _Pragma("unroll") for (int k = 0; k < 2; ++k) dst[m][k] = *(const PG8_LAS bf16x8*)(lds + PG8_SA(b, h) + aoff + m * 2048 + k * 1024); } while (0)
; #define PG8_LDB(dst, b, h) do { _Pragma("unroll") for (int n = 0; n < 2; ++n) _Pragma("unroll") for (int k = 0; k < 2; ++k) dst[n][k] = *(const PG8_LAS bf16x8*)(lds + PG8_SB(b, h) + boff + n * 2048 + k * 1024); } while (0)
; #define PG8_MMA(ai, bj, At, Bt) do { __builtin_amdgcn_s_setprio(1); _Pragma("unroll") for (int m = 0; m < 4; ++m) _Pragma("unroll") for (int n = 0; n < 2; ++n) _Pragma("unroll") for (int k = 0; k < 2; ++k) \
;         acc[ai][bj][m][n] = __builtin_amdgcn_mfma_f32_16x16x32_bf16(Bt[n][k], At[m][k], acc[ai][bj][m][n], 0, 0, 0); __builtin_amdgcn_s_setprio(0); } while (0)
; #define PG8_WAIT_V(n) asm volatile("s_waitcnt vmcnt(" #n ")" ::: "memory")
; #define PG8_WAIT_L(n) asm volatile("s_waitcnt lgkmcnt(" #n ")" ::: "memory")
; #define PG8_BAR __builtin_amdgcn_s_barrier()
; #define PG8_SCHED __builtin_amdgcn_sched_barrier(0)
; template <class Epi, class Sched, bool ALIGN_EPI = false, bool SP2 = false>
; __device__ __forceinline__ void gemm_phase(PG8_LAS unsigned char* lds, const Gemm g, const Sched& S, const Epi& E) {
;     ...
;             PG8_LDB(B0, 1, 0); PG8_LDB(B1, 1, 1); PG8_SCHED; PG8_LDA(At, 1, 0); PG8_STAGE(PG8_SA(0, 1), a2 + hstepA, voffA);
;             PG8_WAIT_V(8); PG8_WAIT_L(0); PG8_BAR; PG8_MMA(0, 0, At, B0); PG8_MMA(0, 1, At, B1); PG8_BAR; PG8_SCHED;
;             PG8_LDA(At, 1, 1); PG8_STAGE(PG8_SB(1, 0), b3, voffB); PG8_STAGE(PG8_SB(1, 1), b3 + hstepB, voffB); PG8_STAGE(PG8_SA(1, 0), a3, voffA);
;             PG8_WAIT_V(8); PG8_WAIT_L(0); PG8_BAR; PG8_MMA(1, 0, At, B0); PG8_MMA(1, 1, At, B1); PG8_BAR; PG8_SCHED;
	s_add_i32 s30, 0, 0x18000
	s_add_i32 s31, 0, 0x1c000
	v_add_u32_e32 v140, s30, v182
	v_add_u32_e32 v166, s31, v182
	ds_read_b128 v[128:131], v140
	ds_read_b128 v[132:135], v140 offset:1024
	ds_read_b128 v[136:139], v140 offset:2048
	ds_read_b128 v[140:143], v140 offset:3072
	ds_read_b128 v[144:147], v166
	ds_read_b128 v[148:151], v166 offset:1024
	ds_read_b128 v[152:155], v166 offset:2048
	ds_read_b128 v[166:169], v166 offset:3072
	s_add_u32 s2, s86, 0x40000
	s_addc_u32 s3, s87, 0
	s_mov_b32 m0, s34
	ds_read_b128 v[170:173], v183 offset:32768
	ds_read_b128 v[174:177], v183 offset:33792
	ds_read_b128 v[178:181], v183 offset:34816
	ds_read_b128 v[184:187], v183 offset:35840
	ds_read_b128 v[188:191], v183 offset:36864
	ds_read_b128 v[198:201], v183 offset:37888
	ds_read_b128 v[202:205], v183 offset:38912
	ds_read_b128 v[206:209], v183 offset:39936
	global_load_lds_dwordx4 v160, s[2:3]
	s_mov_b32 m0, s45
	s_nop 0
	global_load_lds_dwordx4 v158, s[2:3]
	s_waitcnt vmcnt(8)
	s_waitcnt lgkmcnt(0)
	s_barrier
	s_waitcnt lgkmcnt(0)
	v_mfma_f32_16x16x32_bf16 v[124:127], v[128:131], v[170:173], v[124:127]
	v_mfma_f32_16x16x32_bf16 v[120:123], v[136:139], v[170:173], v[120:123]
	v_mfma_f32_16x16x32_bf16 v[108:111], v[128:131], v[178:181], v[108:111]
	v_mfma_f32_16x16x32_bf16 v[104:107], v[136:139], v[178:181], v[104:107]
	v_mfma_f32_16x16x32_bf16 v[92:95], v[128:131], v[188:191], v[92:95]
	v_mfma_f32_16x16x32_bf16 v[88:91], v[136:139], v[188:191], v[88:91]
	v_mfma_f32_16x16x32_bf16 v[76:79], v[128:131], v[202:205], v[76:79]
	v_mfma_f32_16x16x32_bf16 v[72:75], v[136:139], v[202:205], v[72:75]
	v_mfma_f32_16x16x32_bf16 v[124:127], v[132:135], v[174:177], v[124:127]
	v_mfma_f32_16x16x32_bf16 v[120:123], v[140:143], v[174:177], v[120:123]
	v_mfma_f32_16x16x32_bf16 v[108:111], v[132:135], v[184:187], v[108:111]
	v_mfma_f32_16x16x32_bf16 v[104:107], v[140:143], v[184:187], v[104:107]
	v_mfma_f32_16x16x32_bf16 v[92:95], v[132:135], v[198:201], v[92:95]
	v_mfma_f32_16x16x32_bf16 v[88:91], v[140:143], v[198:201], v[88:91]
	v_mfma_f32_16x16x32_bf16 v[76:79], v[132:135], v[206:209], v[76:79]
	v_mfma_f32_16x16x32_bf16 v[72:75], v[140:143], v[206:209], v[72:75]
	v_mfma_f32_16x16x32_bf16 v[116:119], v[144:147], v[170:173], v[116:119]
	v_mfma_f32_16x16x32_bf16 v[112:115], v[152:155], v[170:173], v[112:115]
	v_mfma_f32_16x16x32_bf16 v[100:103], v[144:147], v[178:181], v[100:103]
	v_mfma_f32_16x16x32_bf16 v[96:99], v[152:155], v[178:181], v[96:99]
	v_mfma_f32_16x16x32_bf16 v[84:87], v[144:147], v[188:191], v[84:87]
	v_mfma_f32_16x16x32_bf16 v[80:83], v[152:155], v[188:191], v[80:83]
	v_mfma_f32_16x16x32_bf16 v[68:71], v[144:147], v[202:205], v[68:71]
	v_mfma_f32_16x16x32_bf16 v[64:67], v[152:155], v[202:205], v[64:67]
	v_mfma_f32_16x16x32_bf16 v[116:119], v[148:151], v[174:177], v[116:119]
	v_mfma_f32_16x16x32_bf16 v[112:115], v[166:169], v[174:177], v[112:115]
	v_mfma_f32_16x16x32_bf16 v[100:103], v[148:151], v[184:187], v[100:103]
	v_mfma_f32_16x16x32_bf16 v[96:99], v[166:169], v[184:187], v[96:99]
	v_mfma_f32_16x16x32_bf16 v[84:87], v[148:151], v[198:201], v[84:87]
	v_mfma_f32_16x16x32_bf16 v[80:83], v[166:169], v[198:201], v[80:83]
	v_mfma_f32_16x16x32_bf16 v[68:71], v[148:151], v[206:209], v[68:71]
	v_mfma_f32_16x16x32_bf16 v[64:67], v[166:169], v[206:209], v[64:67]
	s_barrier
	s_add_i32 s2, s30, s19
	s_add_i32 m0, s2, 0xffffff80
	ds_read_b128 v[170:173], v183 offset:49152
	ds_read_b128 v[174:177], v183 offset:50176
	ds_read_b128 v[178:181], v183 offset:51200
	ds_read_b128 v[184:187], v183 offset:52224
	ds_read_b128 v[188:191], v183 offset:53248
	ds_read_b128 v[198:201], v183 offset:54272
	ds_read_b128 v[202:205], v183 offset:55296
	ds_read_b128 v[206:209], v183 offset:56320
	global_load_lds_dwordx4 v192, s[84:85] offset:128
	s_add_i32 m0, s2, 0x1f80
	s_add_u32 s2, s84, 0x40080
	s_addc_u32 s3, s85, 0
	s_add_i32 s30, s31, s19
	global_load_lds_dwordx4 v156, s[84:85] offset:128
	s_mov_b32 m0, s30
	s_nop 0
	global_load_lds_dwordx4 v192, s[2:3]
	s_add_i32 m0, s30, 0x2000
	s_nop 0
	global_load_lds_dwordx4 v156, s[2:3]
	s_add_i32 m0, s63, 0xffffff80
	s_nop 0
	global_load_lds_dwordx4 v160, s[86:87] offset:128
	s_add_i32 m0, s64, 0xffffff80
	s_nop 0
	global_load_lds_dwordx4 v158, s[86:87] offset:128
	s_waitcnt vmcnt(8)
	s_waitcnt lgkmcnt(0)
	s_barrier
	s_waitcnt lgkmcnt(0)
	v_mfma_f32_16x16x32_bf16 v[60:63], v[128:131], v[170:173], v[60:63]
	v_mfma_f32_16x16x32_bf16 v[56:59], v[136:139], v[170:173], v[56:59]
	v_mfma_f32_16x16x32_bf16 v[44:47], v[128:131], v[178:181], v[44:47]
	v_mfma_f32_16x16x32_bf16 v[40:43], v[136:139], v[178:181], v[40:43]
	v_mfma_f32_16x16x32_bf16 v[28:31], v[128:131], v[188:191], v[28:31]
	v_mfma_f32_16x16x32_bf16 v[24:27], v[136:139], v[188:191], v[24:27]
	v_mfma_f32_16x16x32_bf16 v[12:15], v[128:131], v[202:205], v[12:15]
	v_mfma_f32_16x16x32_bf16 v[8:11], v[136:139], v[202:205], v[8:11]
	v_mfma_f32_16x16x32_bf16 v[60:63], v[132:135], v[174:177], v[60:63]
	v_mfma_f32_16x16x32_bf16 v[56:59], v[140:143], v[174:177], v[56:59]
	v_mfma_f32_16x16x32_bf16 v[44:47], v[132:135], v[184:187], v[44:47]
	v_mfma_f32_16x16x32_bf16 v[40:43], v[140:143], v[184:187], v[40:43]
	v_mfma_f32_16x16x32_bf16 v[28:31], v[132:135], v[198:201], v[28:31]
	v_mfma_f32_16x16x32_bf16 v[24:27], v[140:143], v[198:201], v[24:27]
	v_mfma_f32_16x16x32_bf16 v[12:15], v[132:135], v[206:209], v[12:15]
	v_mfma_f32_16x16x32_bf16 v[8:11], v[140:143], v[206:209], v[8:11]
	v_mfma_f32_16x16x32_bf16 v[52:55], v[144:147], v[170:173], v[52:55]
	v_mfma_f32_16x16x32_bf16 v[48:51], v[152:155], v[170:173], v[48:51]
	v_mfma_f32_16x16x32_bf16 v[36:39], v[144:147], v[178:181], v[36:39]
	v_mfma_f32_16x16x32_bf16 v[32:35], v[152:155], v[178:181], v[32:35]
	v_mfma_f32_16x16x32_bf16 v[20:23], v[144:147], v[188:191], v[20:23]
	v_mfma_f32_16x16x32_bf16 v[16:19], v[152:155], v[188:191], v[16:19]
	v_mfma_f32_16x16x32_bf16 v[4:7], v[144:147], v[202:205], v[4:7]
	v_mfma_f32_16x16x32_bf16 v[0:3], v[152:155], v[202:205], v[0:3]
	v_mfma_f32_16x16x32_bf16 v[52:55], v[148:151], v[174:177], v[52:55]
	v_mfma_f32_16x16x32_bf16 v[48:51], v[166:169], v[174:177], v[48:51]
	v_mfma_f32_16x16x32_bf16 v[36:39], v[148:151], v[184:187], v[36:39]
	v_mfma_f32_16x16x32_bf16 v[32:35], v[166:169], v[184:187], v[32:35]
	v_mfma_f32_16x16x32_bf16 v[20:23], v[148:151], v[198:201], v[20:23]
	v_mfma_f32_16x16x32_bf16 v[16:19], v[166:169], v[198:201], v[16:19]
	v_mfma_f32_16x16x32_bf16 v[4:7], v[148:151], v[206:209], v[4:7]
	v_mfma_f32_16x16x32_bf16 v[0:3], v[166:169], v[206:209], v[0:3]
	s_barrier
	s_add_i32 s92, s92, 2
	s_add_u32 s90, s90, 0x100
	s_addc_u32 s91, s91, 0
	s_add_u32 s4, s4, 0x100
	s_addc_u32 s5, s5, 0
	s_cmp_gt_u32 s92, 13
	s_cbranch_scc0 .LBB0_693
	s_and_b64 vcc, exec, s[12:13]
	s_cbranch_vccz .LBB0_696
	s_barrier

; #define PG8_STAGE(bufoff, gbase, voff) do { _Pragma("unroll") for (int _i = 0; _i < 2; ++_i) \
;         __builtin_amdgcn_global_load_lds((const unsigned*)((const char*)(gbase) + (voff)[_i]), (PG8_LAS unsigned*)(lds + (bufoff) + ldsw + _i * 8192), 16, 0, 0); } while (0)
; #define PG8_LDA(dst, b, h) do { _Pragma("unroll") for (int m = 0; m < 4; ++m) _Pragma("unroll") for (int k = 0; k < 2; ++k) dst[m][k] = *(const PG8_LAS bf16x8*)(lds + PG8_SA(b, h) + aoff + m * 2048 + k * 1024); } while (0)
; #define PG8_LDB(dst, b, h) do { _Pragma("unroll") for (int n = 0; n < 2; ++n) _Pragma("unroll") for (int k = 0; k < 2; ++k) dst[n][k] = *(const PG8_LAS bf16x8*)(lds + PG8_SB(b, h) + boff + n * 2048 + k * 1024); } while (0)
; #define PG8_MMA(ai, bj, At, Bt) do { __builtin_amdgcn_s_setprio(1); _Pragma("unroll") for (int m = 0; m < 4; ++m) _Pragma("unroll") for (int n = 0; n < 2; ++n) _Pragma("unroll") for (int k = 0; k < 2; ++k) \
;         acc[ai][bj][m][n] = __builtin_amdgcn_mfma_f32_16x16x32_bf16(Bt[n][k], At[m][k], acc[ai][bj][m][n], 0, 0, 0); __builtin_amdgcn_s_setprio(0); } while (0)
; #define PG8_WAIT_V(n) asm volatile("s_waitcnt vmcnt(" #n ")" ::: "memory")
; #define PG8_WAIT_L(n) asm volatile("s_waitcnt lgkmcnt(" #n ")" ::: "memory")
; #define PG8_BAR __builtin_amdgcn_s_barrier()
; #define PG8_SCHED __builtin_amdgcn_sched_barrier(0)
; template <class Epi, class Sched, bool ALIGN_EPI = false, bool SP2 = false>
; __device__ __forceinline__ void gemm_phase(PG8_LAS unsigned char* lds, const Gemm g, const Sched& S, const Epi& E) {
;     ...
;             const bool last = (t == nt - 2);
;             const char* a1 = cA + (size_t)(t + 1) * kstep;
;             const char* a2 = last ? nA : cA + (size_t)(t + 2) * kstep; const char* b2 = last ? nB : cB + (size_t)(t + 2) * kstep;
;             const char* a3 = a2 + kstep; const char* b3 = b2 + kstep;
;             if (last && has_next) S.a_ready(nxt);
;             if constexpr (SP2) {
;             PG8_LDB(B0, 0, 0); PG8_LDB(B1, 0, 1); PG8_SCHED; PG8_LDA(At, 0, 0); PG8_STAGE(PG8_SA(1, 1), a1 + hstepA, voffA);
;             PG8_WAIT_V(8); PG8_WAIT_L(0); PG8_BAR; PG8_MMA(0, 0, At, B0); PG8_MMA(0, 1, At, B1); PG8_BAR; PG8_SCHED;
;             PG8_LDA(At, 0, 1); PG8_STAGE(PG8_SB(0, 0), b2, voffB); PG8_STAGE(PG8_SB(0, 1), b2 + hstepB, voffB); PG8_STAGE(PG8_SA(0, 0), a2, voffA);
.LBB0_724:
	s_add_i32 s2, s84, 2
	s_add_u32 s3, s82, 0x80
	s_addc_u32 s30, s83, 0
	s_add_i32 s77, 0, 0x10000
	s_cmp_eq_u32 s93, s84
	s_cselect_b32 s85, s5, s30
	s_cselect_b32 s84, s4, s3
	s_cselect_b32 s31, s67, vcc_hi
	s_cselect_b32 s30, s66, vcc_lo
	s_add_i32 s3, 0, 0x14000
	v_add_u32_e32 v136, s77, v247
	v_add_u32_e32 v156, s3, v247
	ds_read_b128 v[112:115], v136
	ds_read_b128 v[124:127], v136 offset:1024
	ds_read_b128 v[128:131], v136 offset:2048
	ds_read_b128 v[136:139], v136 offset:3072
	ds_read_b128 v[144:147], v156
	ds_read_b128 v[148:151], v156 offset:1024
	ds_read_b128 v[152:155], v156 offset:2048
	ds_read_b128 v[156:159], v156 offset:3072
	s_add_i32 m0, s64, 0xc000
	ds_read_b128 v[160:163], v248
	ds_read_b128 v[164:167], v248 offset:1024
	ds_read_b128 v[168:171], v248 offset:2048
	ds_read_b128 v[172:175], v248 offset:3072
	ds_read_b128 v[176:179], v248 offset:4096
	ds_read_b128 v[180:183], v248 offset:5120
	ds_read_b128 v[184:187], v248 offset:6144
	ds_read_b128 v[188:191], v248 offset:7168
	global_load_lds_dwordx4 v206, s[82:83]
	s_add_i32 m0, s64, 0xe000
	s_nop 0
	global_load_lds_dwordx4 v204, s[82:83]
	s_waitcnt vmcnt(8)
	s_waitcnt lgkmcnt(0)
	s_barrier
	s_waitcnt lgkmcnt(0)
	v_mfma_f32_16x16x32_bf16 v[140:143], v[112:115], v[160:163], v[140:143]
	v_mfma_f32_16x16x32_bf16 v[132:135], v[128:131], v[160:163], v[132:135]
	v_mfma_f32_16x16x32_bf16 v[108:111], v[112:115], v[168:171], v[108:111]
	v_mfma_f32_16x16x32_bf16 v[104:107], v[128:131], v[168:171], v[104:107]
	v_mfma_f32_16x16x32_bf16 v[92:95], v[112:115], v[176:179], v[92:95]
	v_mfma_f32_16x16x32_bf16 v[88:91], v[128:131], v[176:179], v[88:91]
	v_mfma_f32_16x16x32_bf16 v[76:79], v[112:115], v[184:187], v[76:79]
	v_mfma_f32_16x16x32_bf16 v[72:75], v[128:131], v[184:187], v[72:75]
	v_mfma_f32_16x16x32_bf16 v[140:143], v[124:127], v[164:167], v[140:143]
	v_mfma_f32_16x16x32_bf16 v[132:135], v[136:139], v[164:167], v[132:135]
	v_mfma_f32_16x16x32_bf16 v[108:111], v[124:127], v[172:175], v[108:111]
	v_mfma_f32_16x16x32_bf16 v[104:107], v[136:139], v[172:175], v[104:107]
	v_mfma_f32_16x16x32_bf16 v[92:95], v[124:127], v[180:183], v[92:95]
	v_mfma_f32_16x16x32_bf16 v[88:91], v[136:139], v[180:183], v[88:91]
	v_mfma_f32_16x16x32_bf16 v[76:79], v[124:127], v[188:191], v[76:79]
	v_mfma_f32_16x16x32_bf16 v[72:75], v[136:139], v[188:191], v[72:75]
	v_mfma_f32_16x16x32_bf16 v[120:123], v[144:147], v[160:163], v[120:123]
	v_mfma_f32_16x16x32_bf16 v[116:119], v[152:155], v[160:163], v[116:119]
	v_mfma_f32_16x16x32_bf16 v[100:103], v[144:147], v[168:171], v[100:103]
	v_mfma_f32_16x16x32_bf16 v[96:99], v[152:155], v[168:171], v[96:99]
	v_mfma_f32_16x16x32_bf16 v[84:87], v[144:147], v[176:179], v[84:87]
	v_mfma_f32_16x16x32_bf16 v[80:83], v[152:155], v[176:179], v[80:83]
	v_mfma_f32_16x16x32_bf16 v[68:71], v[144:147], v[184:187], v[68:71]
	v_mfma_f32_16x16x32_bf16 v[64:67], v[152:155], v[184:187], v[64:67]
	v_mfma_f32_16x16x32_bf16 v[120:123], v[148:151], v[164:167], v[120:123]
	v_mfma_f32_16x16x32_bf16 v[116:119], v[156:159], v[164:167], v[116:119]
	v_mfma_f32_16x16x32_bf16 v[100:103], v[148:151], v[172:175], v[100:103]
	v_mfma_f32_16x16x32_bf16 v[96:99], v[156:159], v[172:175], v[96:99]
	v_mfma_f32_16x16x32_bf16 v[84:87], v[148:151], v[180:183], v[84:87]
	v_mfma_f32_16x16x32_bf16 v[80:83], v[156:159], v[180:183], v[80:83]
	v_mfma_f32_16x16x32_bf16 v[68:71], v[148:151], v[188:191], v[68:71]
	v_mfma_f32_16x16x32_bf16 v[64:67], v[156:159], v[188:191], v[64:67]
	s_barrier
	s_add_i32 s77, s77, s63
	v_lshl_add_u64 v[208:209], s[30:31], 0, v[192:193]
	s_mov_b32 m0, s77
	ds_read_b128 v[160:163], v248 offset:16384
	ds_read_b128 v[164:167], v248 offset:17408
	ds_read_b128 v[168:171], v248 offset:18432
	ds_read_b128 v[172:175], v248 offset:19456
	ds_read_b128 v[176:179], v248 offset:20480
	ds_read_b128 v[180:183], v248 offset:21504
	ds_read_b128 v[184:187], v248 offset:22528
	ds_read_b128 v[188:191], v248 offset:23552
	global_load_lds_dwordx4 v192, s[30:31]
	s_add_i32 m0, s77, 0x2000
	v_lshl_add_u64 v[210:211], s[30:31], 0, v[198:199]
	global_load_lds_dwordx4 v198, s[30:31]
	s_add_u32 s30, s30, s45
	s_addc_u32 s31, s31, 0
	s_add_i32 s3, s3, s63
	v_lshl_add_u64 v[212:213], s[30:31], 0, v[192:193]
	s_mov_b32 m0, s3
	v_lshl_add_u64 v[214:215], s[30:31], 0, v[198:199]
	global_load_lds_dwordx4 v192, s[30:31]
	s_add_i32 m0, s3, 0x2000
	s_nop 0
	global_load_lds_dwordx4 v198, s[30:31]
	s_mov_b32 m0, s64
	s_nop 0
	global_load_lds_dwordx4 v202, s[84:85]
	s_mov_b32 m0, s65
	s_nop 0
	global_load_lds_dwordx4 v200, s[84:85]
	s_waitcnt vmcnt(8)
	s_waitcnt lgkmcnt(0)
	s_barrier
; #define PG8_STAGE(bufoff, gbase, voff) do { _Pragma("unroll") for (int _i = 0; _i < 2; ++_i) \
;         __builtin_amdgcn_global_load_lds((const unsigned*)((const char*)(gbase) + (voff)[_i]), (PG8_LAS unsigned*)(lds + (bufoff) + ldsw + _i * 8192), 16, 0, 0); } while (0)
; #define PG8_LDA(dst, b, h) do { _Pragma("unroll") for (int m = 0; m < 4; ++m) _Pragma("unroll") for (int k = 0; k < 2; ++k) dst[m][k] = *(const PG8_LAS bf16x8*)(lds + PG8_SA(b, h) + aoff + m * 2048 + k * 1024); } while (0)
; #define PG8_LDB(dst, b, h) do { _Pragma("unroll") for (int n = 0; n < 2; ++n) _Pragma("unroll") for (int k = 0; k < 2; ++k) dst[n][k] = *(const PG8_LAS bf16x8*)(lds + PG8_SB(b, h) + boff + n * 2048 + k * 1024); } while (0)
; #define PG8_MMA(ai, bj, At, Bt) do { __builtin_amdgcn_s_setprio(1); _Pragma("unroll") for (int m = 0; m < 4; ++m) _Pragma("unroll") for (int n = 0; n < 2; ++n) _Pragma("unroll") for (int k = 0; k < 2; ++k) \
;         acc[ai][bj][m][n] = __builtin_amdgcn_mfma_f32_16x16x32_bf16(Bt[n][k], At[m][k], acc[ai][bj][m][n], 0, 0, 0); __builtin_amdgcn_s_setprio(0); } while (0)
; #define PG8_WAIT_V(n) asm volatile("s_waitcnt vmcnt(" #n ")" ::: "memory")
; #define PG8_WAIT_L(n) asm volatile("s_waitcnt lgkmcnt(" #n ")" ::: "memory")
; #define PG8_BAR __builtin_amdgcn_s_barrier()
; #define PG8_SCHED __builtin_amdgcn_sched_barrier(0)
; template <class Epi, class Sched, bool ALIGN_EPI = false, bool SP2 = false>
; __device__ __forceinline__ void gemm_phase(PG8_LAS unsigned char* lds, const Gemm g, const Sched& S, const Epi& E) {
;     ...
;             PG8_WAIT_V(8); PG8_WAIT_L(0); PG8_BAR; PG8_MMA(1, 0, At, B0); PG8_MMA(1, 1, At, B1); PG8_BAR; PG8_SCHED;
;             PG8_LDB(B0, 1, 0); PG8_LDB(B1, 1, 1); PG8_SCHED; PG8_LDA(At, 1, 0); PG8_STAGE(PG8_SA(0, 1), a2 + hstepA, voffA);
;             PG8_WAIT_V(8); PG8_WAIT_L(0); PG8_BAR; PG8_MMA(0, 0, At, B0); PG8_MMA(0, 1, At, B1); PG8_BAR; PG8_SCHED;
	s_waitcnt lgkmcnt(0)
	v_mfma_f32_16x16x32_bf16 v[60:63], v[112:115], v[160:163], v[60:63]
	v_mfma_f32_16x16x32_bf16 v[56:59], v[128:131], v[160:163], v[56:59]
	v_mfma_f32_16x16x32_bf16 v[44:47], v[112:115], v[168:171], v[44:47]
	v_mfma_f32_16x16x32_bf16 v[40:43], v[128:131], v[168:171], v[40:43]
	v_mfma_f32_16x16x32_bf16 v[28:31], v[112:115], v[176:179], v[28:31]
	v_mfma_f32_16x16x32_bf16 v[24:27], v[128:131], v[176:179], v[24:27]
	v_mfma_f32_16x16x32_bf16 v[12:15], v[112:115], v[184:187], v[12:15]
	v_mfma_f32_16x16x32_bf16 v[8:11], v[128:131], v[184:187], v[8:11]
	v_mfma_f32_16x16x32_bf16 v[60:63], v[124:127], v[164:167], v[60:63]
	v_mfma_f32_16x16x32_bf16 v[56:59], v[136:139], v[164:167], v[56:59]
	v_mfma_f32_16x16x32_bf16 v[44:47], v[124:127], v[172:175], v[44:47]
	v_mfma_f32_16x16x32_bf16 v[40:43], v[136:139], v[172:175], v[40:43]
	v_mfma_f32_16x16x32_bf16 v[28:31], v[124:127], v[180:183], v[28:31]
	v_mfma_f32_16x16x32_bf16 v[24:27], v[136:139], v[180:183], v[24:27]
	v_mfma_f32_16x16x32_bf16 v[12:15], v[124:127], v[188:191], v[12:15]
	v_mfma_f32_16x16x32_bf16 v[8:11], v[136:139], v[188:191], v[8:11]
	v_mfma_f32_16x16x32_bf16 v[52:55], v[144:147], v[160:163], v[52:55]
	v_mfma_f32_16x16x32_bf16 v[48:51], v[152:155], v[160:163], v[48:51]
	v_mfma_f32_16x16x32_bf16 v[36:39], v[144:147], v[168:171], v[36:39]
	v_mfma_f32_16x16x32_bf16 v[32:35], v[152:155], v[168:171], v[32:35]
	v_mfma_f32_16x16x32_bf16 v[20:23], v[144:147], v[176:179], v[20:23]
	v_mfma_f32_16x16x32_bf16 v[16:19], v[152:155], v[176:179], v[16:19]
	v_mfma_f32_16x16x32_bf16 v[4:7], v[144:147], v[184:187], v[4:7]
	v_mfma_f32_16x16x32_bf16 v[0:3], v[152:155], v[184:187], v[0:3]
	v_mfma_f32_16x16x32_bf16 v[52:55], v[148:151], v[164:167], v[52:55]
	v_mfma_f32_16x16x32_bf16 v[48:51], v[156:159], v[164:167], v[48:51]
	v_mfma_f32_16x16x32_bf16 v[36:39], v[148:151], v[172:175], v[36:39]
	v_mfma_f32_16x16x32_bf16 v[32:35], v[156:159], v[172:175], v[32:35]
	v_mfma_f32_16x16x32_bf16 v[20:23], v[148:151], v[180:183], v[20:23]
	v_mfma_f32_16x16x32_bf16 v[16:19], v[156:159], v[180:183], v[16:19]
	v_mfma_f32_16x16x32_bf16 v[4:7], v[148:151], v[188:191], v[4:7]
	v_mfma_f32_16x16x32_bf16 v[0:3], v[156:159], v[188:191], v[0:3]
	s_barrier
	s_add_i32 s3, 0, 0x18000
	s_add_i32 s77, 0, 0x1c000
	v_add_u32_e32 v136, s3, v247
	v_add_u32_e32 v156, s77, v247
	ds_read_b128 v[112:115], v136
	ds_read_b128 v[124:127], v136 offset:1024
	ds_read_b128 v[128:131], v136 offset:2048
	ds_read_b128 v[136:139], v136 offset:3072
	ds_read_b128 v[144:147], v156
	ds_read_b128 v[148:151], v156 offset:1024
	ds_read_b128 v[152:155], v156 offset:2048
	ds_read_b128 v[156:159], v156 offset:3072
	s_add_u32 s30, s84, s10
	s_addc_u32 s31, s85, 0
	s_mov_b32 m0, s80
	ds_read_b128 v[160:163], v248 offset:32768
	ds_read_b128 v[164:167], v248 offset:33792
	ds_read_b128 v[168:171], v248 offset:34816
	ds_read_b128 v[172:175], v248 offset:35840
	ds_read_b128 v[176:179], v248 offset:36864
	ds_read_b128 v[180:183], v248 offset:37888
	ds_read_b128 v[184:187], v248 offset:38912
	ds_read_b128 v[188:191], v248 offset:39936
	global_load_lds_dwordx4 v202, s[30:31]
	s_mov_b32 m0, s86
	s_nop 0
	global_load_lds_dwordx4 v200, s[30:31]
	s_waitcnt vmcnt(8)
	s_waitcnt lgkmcnt(0)
	s_barrier
	s_waitcnt lgkmcnt(0)
	v_mfma_f32_16x16x32_bf16 v[140:143], v[112:115], v[160:163], v[140:143]
	v_mfma_f32_16x16x32_bf16 v[132:135], v[128:131], v[160:163], v[132:135]
	v_mfma_f32_16x16x32_bf16 v[108:111], v[112:115], v[168:171], v[108:111]
	v_mfma_f32_16x16x32_bf16 v[104:107], v[128:131], v[168:171], v[104:107]
	v_mfma_f32_16x16x32_bf16 v[92:95], v[112:115], v[176:179], v[92:95]
	v_mfma_f32_16x16x32_bf16 v[88:91], v[128:131], v[176:179], v[88:91]
	v_mfma_f32_16x16x32_bf16 v[76:79], v[112:115], v[184:187], v[76:79]
	v_mfma_f32_16x16x32_bf16 v[72:75], v[128:131], v[184:187], v[72:75]
	v_mfma_f32_16x16x32_bf16 v[140:143], v[124:127], v[164:167], v[140:143]
	v_mfma_f32_16x16x32_bf16 v[132:135], v[136:139], v[164:167], v[132:135]
	v_mfma_f32_16x16x32_bf16 v[108:111], v[124:127], v[172:175], v[108:111]
	v_mfma_f32_16x16x32_bf16 v[104:107], v[136:139], v[172:175], v[104:107]
	v_mfma_f32_16x16x32_bf16 v[92:95], v[124:127], v[180:183], v[92:95]
	v_mfma_f32_16x16x32_bf16 v[88:91], v[136:139], v[180:183], v[88:91]
	v_mfma_f32_16x16x32_bf16 v[76:79], v[124:127], v[188:191], v[76:79]
	v_mfma_f32_16x16x32_bf16 v[72:75], v[136:139], v[188:191], v[72:75]
	v_mfma_f32_16x16x32_bf16 v[120:123], v[144:147], v[160:163], v[120:123]
	v_mfma_f32_16x16x32_bf16 v[116:119], v[152:155], v[160:163], v[116:119]
	v_mfma_f32_16x16x32_bf16 v[100:103], v[144:147], v[168:171], v[100:103]
	v_mfma_f32_16x16x32_bf16 v[96:99], v[152:155], v[168:171], v[96:99]
	v_mfma_f32_16x16x32_bf16 v[84:87], v[144:147], v[176:179], v[84:87]
	v_mfma_f32_16x16x32_bf16 v[80:83], v[152:155], v[176:179], v[80:83]
	v_mfma_f32_16x16x32_bf16 v[68:71], v[144:147], v[184:187], v[68:71]
	v_mfma_f32_16x16x32_bf16 v[64:67], v[152:155], v[184:187], v[64:67]
	v_mfma_f32_16x16x32_bf16 v[120:123], v[148:151], v[164:167], v[120:123]
	v_mfma_f32_16x16x32_bf16 v[116:119], v[156:159], v[164:167], v[116:119]
	v_mfma_f32_16x16x32_bf16 v[100:103], v[148:151], v[172:175], v[100:103]
	v_mfma_f32_16x16x32_bf16 v[96:99], v[156:159], v[172:175], v[96:99]
	v_mfma_f32_16x16x32_bf16 v[84:87], v[148:151], v[180:183], v[84:87]
	v_mfma_f32_16x16x32_bf16 v[80:83], v[156:159], v[180:183], v[80:83]
	v_mfma_f32_16x16x32_bf16 v[68:71], v[148:151], v[188:191], v[68:71]
	v_mfma_f32_16x16x32_bf16 v[64:67], v[156:159], v[188:191], v[64:67]
	s_barrier
; #define PG8_STAGE(bufoff, gbase, voff) do { _Pragma("unroll") for (int _i = 0; _i < 2; ++_i) \
;         __builtin_amdgcn_global_load_lds((const unsigned*)((const char*)(gbase) + (voff)[_i]), (PG8_LAS unsigned*)(lds + (bufoff) + ldsw + _i * 8192), 16, 0, 0); } while (0)
; #define PG8_LDA(dst, b, h) do { _Pragma("unroll") for (int m = 0; m < 4; ++m) _Pragma("unroll") for (int k = 0; k < 2; ++k) dst[m][k] = *(const PG8_LAS bf16x8*)(lds + PG8_SA(b, h) + aoff + m * 2048 + k * 1024); } while (0)
; #define PG8_MMA(ai, bj, At, Bt) do { __builtin_amdgcn_s_setprio(1); _Pragma("unroll") for (int m = 0; m < 4; ++m) _Pragma("unroll") for (int n = 0; n < 2; ++n) _Pragma("unroll") for (int k = 0; k < 2; ++k) \
;         acc[ai][bj][m][n] = __builtin_amdgcn_mfma_f32_16x16x32_bf16(Bt[n][k], At[m][k], acc[ai][bj][m][n], 0, 0, 0); __builtin_amdgcn_s_setprio(0); } while (0)
; #define PG8_WAIT_V(n) asm volatile("s_waitcnt vmcnt(" #n ")" ::: "memory")
; #define PG8_WAIT_L(n) asm volatile("s_waitcnt lgkmcnt(" #n ")" ::: "memory")
; #define PG8_BAR __builtin_amdgcn_s_barrier()
; #define PG8_SCHED __builtin_amdgcn_sched_barrier(0)
; template <class Epi, class Sched, bool ALIGN_EPI = false, bool SP2 = false>
; __device__ __forceinline__ void gemm_phase(PG8_LAS unsigned char* lds, const Gemm g, const Sched& S, const Epi& E) {
;     ...
;             PG8_LDA(At, 1, 1); PG8_STAGE(PG8_SB(1, 0), b3, voffB); PG8_STAGE(PG8_SB(1, 1), b3 + hstepB, voffB); PG8_STAGE(PG8_SA(1, 0), a3, voffA);
;             PG8_WAIT_V(8); PG8_WAIT_L(0); PG8_BAR; PG8_MMA(1, 0, At, B0); PG8_MMA(1, 1, At, B1); PG8_BAR; PG8_SCHED;
	s_add_i32 s3, s3, s63
	v_lshl_add_u64 v[208:209], v[208:209], 0, s[36:37]
	s_mov_b32 m0, s3
	ds_read_b128 v[160:163], v248 offset:49152
	ds_read_b128 v[164:167], v248 offset:50176
	ds_read_b128 v[168:171], v248 offset:51200
	ds_read_b128 v[172:175], v248 offset:52224
	ds_read_b128 v[176:179], v248 offset:53248
	ds_read_b128 v[180:183], v248 offset:54272
	ds_read_b128 v[184:187], v248 offset:55296
	ds_read_b128 v[188:191], v248 offset:56320
	global_load_lds_dwordx4 v[208:209], off
	v_lshl_add_u64 v[208:209], v[210:211], 0, s[36:37]
	s_add_i32 m0, s3, 0x2000
	s_add_i32 s3, s77, s63
	global_load_lds_dwordx4 v[208:209], off
	v_lshl_add_u64 v[208:209], v[212:213], 0, s[36:37]
	s_mov_b32 m0, s3
	s_nop 0
	global_load_lds_dwordx4 v[208:209], off
	v_lshl_add_u64 v[208:209], v[214:215], 0, s[36:37]
	s_add_i32 m0, s3, 0x2000
	s_nop 0
	global_load_lds_dwordx4 v[208:209], off
	s_add_i32 m0, s91, 0xffffff80
	s_nop 0
	global_load_lds_dwordx4 v202, s[84:85] offset:128
	s_add_i32 m0, s92, 0xffffff80
	s_nop 0
	global_load_lds_dwordx4 v200, s[84:85] offset:128
	s_waitcnt vmcnt(8)
	s_waitcnt lgkmcnt(0)
	s_barrier
	s_waitcnt lgkmcnt(0)
	v_mfma_f32_16x16x32_bf16 v[60:63], v[112:115], v[160:163], v[60:63]
	v_mfma_f32_16x16x32_bf16 v[56:59], v[128:131], v[160:163], v[56:59]
	v_mfma_f32_16x16x32_bf16 v[44:47], v[112:115], v[168:171], v[44:47]
	v_mfma_f32_16x16x32_bf16 v[40:43], v[128:131], v[168:171], v[40:43]
	v_mfma_f32_16x16x32_bf16 v[28:31], v[112:115], v[176:179], v[28:31]
	v_mfma_f32_16x16x32_bf16 v[24:27], v[128:131], v[176:179], v[24:27]
	v_mfma_f32_16x16x32_bf16 v[12:15], v[112:115], v[184:187], v[12:15]
	v_mfma_f32_16x16x32_bf16 v[8:11], v[128:131], v[184:187], v[8:11]
	v_mfma_f32_16x16x32_bf16 v[60:63], v[124:127], v[164:167], v[60:63]
	v_mfma_f32_16x16x32_bf16 v[56:59], v[136:139], v[164:167], v[56:59]
	v_mfma_f32_16x16x32_bf16 v[44:47], v[124:127], v[172:175], v[44:47]
	v_mfma_f32_16x16x32_bf16 v[40:43], v[136:139], v[172:175], v[40:43]
	v_mfma_f32_16x16x32_bf16 v[28:31], v[124:127], v[180:183], v[28:31]
	v_mfma_f32_16x16x32_bf16 v[24:27], v[136:139], v[180:183], v[24:27]
	v_mfma_f32_16x16x32_bf16 v[12:15], v[124:127], v[188:191], v[12:15]
	v_mfma_f32_16x16x32_bf16 v[8:11], v[136:139], v[188:191], v[8:11]
	v_mfma_f32_16x16x32_bf16 v[52:55], v[144:147], v[160:163], v[52:55]
	v_mfma_f32_16x16x32_bf16 v[48:51], v[152:155], v[160:163], v[48:51]
	v_mfma_f32_16x16x32_bf16 v[36:39], v[144:147], v[168:171], v[36:39]
	v_mfma_f32_16x16x32_bf16 v[32:35], v[152:155], v[168:171], v[32:35]
	v_mfma_f32_16x16x32_bf16 v[20:23], v[144:147], v[176:179], v[20:23]
	v_mfma_f32_16x16x32_bf16 v[16:19], v[152:155], v[176:179], v[16:19]
	v_mfma_f32_16x16x32_bf16 v[4:7], v[144:147], v[184:187], v[4:7]
	v_mfma_f32_16x16x32_bf16 v[0:3], v[152:155], v[184:187], v[0:3]
	v_mfma_f32_16x16x32_bf16 v[52:55], v[148:151], v[164:167], v[52:55]
	v_mfma_f32_16x16x32_bf16 v[48:51], v[156:159], v[164:167], v[48:51]
	v_mfma_f32_16x16x32_bf16 v[36:39], v[148:151], v[172:175], v[36:39]
	v_mfma_f32_16x16x32_bf16 v[32:35], v[156:159], v[172:175], v[32:35]
	v_mfma_f32_16x16x32_bf16 v[20:23], v[148:151], v[180:183], v[20:23]
	v_mfma_f32_16x16x32_bf16 v[16:19], v[156:159], v[180:183], v[16:19]
	v_mfma_f32_16x16x32_bf16 v[4:7], v[148:151], v[188:191], v[4:7]
	v_mfma_f32_16x16x32_bf16 v[0:3], v[156:159], v[188:191], v[0:3]
	s_barrier
	s_add_u32 vcc_lo, vcc_lo, 0x100
	s_addc_u32 vcc_hi, vcc_hi, 0
	s_add_u32 s82, s82, 0x100
	s_addc_u32 s83, s83, 0
	s_cmp_ge_u32 s2, s87
	s_mov_b32 s84, s2
	s_cbranch_scc0 .LBB0_724
	s_and_b64 vcc, exec, s[16:17]
	s_cbranch_vccz .LBB0_727
	s_barrier

; #define PG8_STAGE(bufoff, gbase, voff) do { _Pragma("unroll") for (int _i = 0; _i < 2; ++_i) \
;         __builtin_amdgcn_global_load_lds((const unsigned*)((const char*)(gbase) + (voff)[_i]), (PG8_LAS unsigned*)(lds + (bufoff) + ldsw + _i * 8192), 16, 0, 0); } while (0)
; #define PG8_LDA(dst, b, h) do { _Pragma("unroll") for (int m = 0; m < 4; ++m) _Pragma("unroll") for (int k = 0; k < 2; ++k) dst[m][k] = *(const PG8_LAS bf16x8*)(lds + PG8_SA(b, h) + aoff + m * 2048 + k * 1024); } while (0)
; #define PG8_LDB(dst, b, h) do { _Pragma("unroll") for (int n = 0; n < 2; ++n) _Pragma("unroll") for (int k = 0; k < 2; ++k) dst[n][k] = *(const PG8_LAS bf16x8*)(lds + PG8_SB(b, h) + boff + n * 2048 + k * 1024); } while (0)
; #define PG8_MMA(ai, bj, At, Bt) do { __builtin_amdgcn_s_setprio(1); _Pragma("unroll") for (int m = 0; m < 4; ++m) _Pragma("unroll") for (int n = 0; n < 2; ++n) _Pragma("unroll") for (int k = 0; k < 2; ++k) \
;         acc[ai][bj][m][n] = __builtin_amdgcn_mfma_f32_16x16x32_bf16(Bt[n][k], At[m][k], acc[ai][bj][m][n], 0, 0, 0); __builtin_amdgcn_s_setprio(0); } while (0)
; #define PG8_WAIT_V(n) asm volatile("s_waitcnt vmcnt(" #n ")" ::: "memory")
; #define PG8_WAIT_L(n) asm volatile("s_waitcnt lgkmcnt(" #n ")" ::: "memory")
; template <class Epi, class Sched, bool ALIGN_EPI = false, bool SP2 = false>
; __device__ __forceinline__ void gemm_phase(PG8_LAS unsigned char* lds, const Gemm g, const Sched& S, const Epi& E) {
;     ...
;             const bool last = (t == nt - 2);
;             const char* a1 = cA + (size_t)(t + 1) * kstep;
;             const char* a2 = last ? nA : cA + (size_t)(t + 2) * kstep; const char* b2 = last ? nB : cB + (size_t)(t + 2) * kstep;
;             const char* a3 = a2 + kstep; const char* b3 = b2 + kstep;
;             if (last && has_next) S.a_ready(nxt);
;             if constexpr (SP2) {
;             PG8_LDB(B0, 0, 0); PG8_LDB(B1, 0, 1); PG8_SCHED; PG8_LDA(At, 0, 0); PG8_STAGE(PG8_SA(1, 1), a1 + hstepA, voffA);
;             PG8_WAIT_V(8); PG8_WAIT_L(0); PG8_BAR; PG8_MMA(0, 0, At, B0); PG8_MMA(0, 1, At, B1); PG8_BAR; PG8_SCHED;
;             PG8_LDA(At, 0, 1); PG8_STAGE(PG8_SB(0, 0), b2, voffB); PG8_STAGE(PG8_SB(0, 1), b2 + hstepB, voffB); PG8_STAGE(PG8_SA(0, 0), a2, voffA);
;             PG8_WAIT_V(8); PG8_WAIT_L(0); PG8_BAR; PG8_MMA(1, 0, At, B0); PG8_MMA(1, 1, At, B1); PG8_BAR; PG8_SCHED;
.LBB0_766:
	s_add_i32 s2, s82, 2
	s_add_u32 s4, s66, 0x100
	s_addc_u32 s5, s67, 0
	s_add_i32 s3, 0, 0x10000
	s_cmp_eq_u32 s88, s82
	s_cselect_b32 s83, s15, s5
	s_cselect_b32 s82, s14, s4
	s_cselect_b32 s97, s17, s94
	s_cselect_b32 s96, s16, s93
	s_add_i32 s30, 0, 0x14000
	v_add_u32_e32 v140, s3, v222
	v_add_u32_e32 v156, s30, v222
	ds_read_b128 v[128:131], v140
	ds_read_b128 v[132:135], v140 offset:1024
	ds_read_b128 v[136:139], v140 offset:2048
	ds_read_b128 v[140:143], v140 offset:3072
	ds_read_b128 v[144:147], v156
	ds_read_b128 v[148:151], v156 offset:1024
	ds_read_b128 v[152:155], v156 offset:2048
	ds_read_b128 v[156:159], v156 offset:3072
	s_add_i32 m0, s62, 0xc000
	ds_read_b128 v[160:163], v223
	ds_read_b128 v[164:167], v223 offset:1024
	ds_read_b128 v[168:171], v223 offset:2048
	ds_read_b128 v[172:175], v223 offset:3072
	ds_read_b128 v[176:179], v223 offset:4096
	ds_read_b128 v[180:183], v223 offset:5120
	ds_read_b128 v[184:187], v223 offset:6144
	ds_read_b128 v[188:191], v223 offset:7168
	global_load_lds_dwordx4 v206, s[66:67]
	s_add_i32 m0, s62, 0xe000
	s_nop 0
	global_load_lds_dwordx4 v204, s[66:67]
	s_waitcnt vmcnt(8)
	s_waitcnt lgkmcnt(0)
	s_barrier
	s_waitcnt lgkmcnt(0)
	v_mfma_f32_16x16x32_bf16 v[124:127], v[128:131], v[160:163], v[124:127]
	v_mfma_f32_16x16x32_bf16 v[120:123], v[136:139], v[160:163], v[120:123]
	v_mfma_f32_16x16x32_bf16 v[112:115], v[128:131], v[168:171], v[112:115]
	v_mfma_f32_16x16x32_bf16 v[104:107], v[136:139], v[168:171], v[104:107]
	v_mfma_f32_16x16x32_bf16 v[96:99], v[128:131], v[176:179], v[96:99]
	v_mfma_f32_16x16x32_bf16 v[88:91], v[136:139], v[176:179], v[88:91]
	v_mfma_f32_16x16x32_bf16 v[80:83], v[128:131], v[184:187], v[80:83]
	v_mfma_f32_16x16x32_bf16 v[72:75], v[136:139], v[184:187], v[72:75]
	v_mfma_f32_16x16x32_bf16 v[124:127], v[132:135], v[164:167], v[124:127]
	v_mfma_f32_16x16x32_bf16 v[120:123], v[140:143], v[164:167], v[120:123]
	v_mfma_f32_16x16x32_bf16 v[112:115], v[132:135], v[172:175], v[112:115]
	v_mfma_f32_16x16x32_bf16 v[104:107], v[140:143], v[172:175], v[104:107]
	v_mfma_f32_16x16x32_bf16 v[96:99], v[132:135], v[180:183], v[96:99]
	v_mfma_f32_16x16x32_bf16 v[88:91], v[140:143], v[180:183], v[88:91]
	v_mfma_f32_16x16x32_bf16 v[80:83], v[132:135], v[188:191], v[80:83]
	v_mfma_f32_16x16x32_bf16 v[72:75], v[140:143], v[188:191], v[72:75]
	v_mfma_f32_16x16x32_bf16 v[116:119], v[144:147], v[160:163], v[116:119]
	v_mfma_f32_16x16x32_bf16 v[108:111], v[152:155], v[160:163], v[108:111]
	v_mfma_f32_16x16x32_bf16 v[100:103], v[144:147], v[168:171], v[100:103]
	v_mfma_f32_16x16x32_bf16 v[92:95], v[152:155], v[168:171], v[92:95]
	v_mfma_f32_16x16x32_bf16 v[84:87], v[144:147], v[176:179], v[84:87]
	v_mfma_f32_16x16x32_bf16 v[76:79], v[152:155], v[176:179], v[76:79]
	v_mfma_f32_16x16x32_bf16 v[68:71], v[144:147], v[184:187], v[68:71]
	v_mfma_f32_16x16x32_bf16 v[64:67], v[152:155], v[184:187], v[64:67]
	v_mfma_f32_16x16x32_bf16 v[116:119], v[148:151], v[164:167], v[116:119]
	v_mfma_f32_16x16x32_bf16 v[108:111], v[156:159], v[164:167], v[108:111]
	v_mfma_f32_16x16x32_bf16 v[100:103], v[148:151], v[172:175], v[100:103]
	v_mfma_f32_16x16x32_bf16 v[92:95], v[156:159], v[172:175], v[92:95]
	v_mfma_f32_16x16x32_bf16 v[84:87], v[148:151], v[180:183], v[84:87]
	v_mfma_f32_16x16x32_bf16 v[76:79], v[156:159], v[180:183], v[76:79]
	v_mfma_f32_16x16x32_bf16 v[68:71], v[148:151], v[188:191], v[68:71]
	v_mfma_f32_16x16x32_bf16 v[64:67], v[156:159], v[188:191], v[64:67]
	s_barrier
	s_add_i32 s3, s3, s49
	s_mov_b32 m0, s3
	ds_read_b128 v[160:163], v223 offset:16384
	ds_read_b128 v[164:167], v223 offset:17408
	ds_read_b128 v[168:171], v223 offset:18432
	ds_read_b128 v[172:175], v223 offset:19456
	ds_read_b128 v[176:179], v223 offset:20480
	ds_read_b128 v[180:183], v223 offset:21504
	ds_read_b128 v[184:187], v223 offset:22528
	ds_read_b128 v[188:191], v223 offset:23552
	global_load_lds_dwordx4 v192, s[96:97]
	s_add_i32 m0, s3, 0x2000
	s_add_u32 s66, s96, s34
	s_addc_u32 s67, s97, 0
	s_add_i32 s3, s30, s49
	global_load_lds_dwordx4 v198, s[96:97]
	v_lshl_add_u64 v[212:213], s[66:67], 0, v[192:193]
	s_mov_b32 m0, s3
	v_lshl_add_u64 v[214:215], s[66:67], 0, v[198:199]
	global_load_lds_dwordx4 v192, s[66:67]
	s_add_i32 m0, s3, 0x2000
	s_nop 0
	global_load_lds_dwordx4 v198, s[66:67]
	s_mov_b32 m0, s62
	s_nop 0
	global_load_lds_dwordx4 v202, s[82:83]
	s_mov_b32 m0, s63
	s_nop 0
	global_load_lds_dwordx4 v200, s[82:83]
	s_waitcnt vmcnt(8)
	s_waitcnt lgkmcnt(0)
	s_barrier
	s_waitcnt lgkmcnt(0)
	v_mfma_f32_16x16x32_bf16 v[60:63], v[128:131], v[160:163], v[60:63]
	v_mfma_f32_16x16x32_bf16 v[56:59], v[136:139], v[160:163], v[56:59]
	v_mfma_f32_16x16x32_bf16 v[48:51], v[128:131], v[168:171], v[48:51]
	v_mfma_f32_16x16x32_bf16 v[40:43], v[136:139], v[168:171], v[40:43]
	v_mfma_f32_16x16x32_bf16 v[32:35], v[128:131], v[176:179], v[32:35]
	v_mfma_f32_16x16x32_bf16 v[24:27], v[136:139], v[176:179], v[24:27]
	v_mfma_f32_16x16x32_bf16 v[16:19], v[128:131], v[184:187], v[16:19]
	v_mfma_f32_16x16x32_bf16 v[8:11], v[136:139], v[184:187], v[8:11]
	v_mfma_f32_16x16x32_bf16 v[60:63], v[132:135], v[164:167], v[60:63]
	v_mfma_f32_16x16x32_bf16 v[56:59], v[140:143], v[164:167], v[56:59]
	v_mfma_f32_16x16x32_bf16 v[48:51], v[132:135], v[172:175], v[48:51]
	v_mfma_f32_16x16x32_bf16 v[40:43], v[140:143], v[172:175], v[40:43]
	v_mfma_f32_16x16x32_bf16 v[32:35], v[132:135], v[180:183], v[32:35]
	v_mfma_f32_16x16x32_bf16 v[24:27], v[140:143], v[180:183], v[24:27]
	v_mfma_f32_16x16x32_bf16 v[16:19], v[132:135], v[188:191], v[16:19]
	v_mfma_f32_16x16x32_bf16 v[8:11], v[140:143], v[188:191], v[8:11]
	v_mfma_f32_16x16x32_bf16 v[52:55], v[144:147], v[160:163], v[52:55]
	v_mfma_f32_16x16x32_bf16 v[44:47], v[152:155], v[160:163], v[44:47]
	v_mfma_f32_16x16x32_bf16 v[36:39], v[144:147], v[168:171], v[36:39]
	v_mfma_f32_16x16x32_bf16 v[28:31], v[152:155], v[168:171], v[28:31]
	v_mfma_f32_16x16x32_bf16 v[20:23], v[144:147], v[176:179], v[20:23]
	v_mfma_f32_16x16x32_bf16 v[12:15], v[152:155], v[176:179], v[12:15]
	v_mfma_f32_16x16x32_bf16 v[4:7], v[144:147], v[184:187], v[4:7]
	v_mfma_f32_16x16x32_bf16 v[0:3], v[152:155], v[184:187], v[0:3]
	v_mfma_f32_16x16x32_bf16 v[52:55], v[148:151], v[164:167], v[52:55]
	v_mfma_f32_16x16x32_bf16 v[44:47], v[156:159], v[164:167], v[44:47]
	v_mfma_f32_16x16x32_bf16 v[36:39], v[148:151], v[172:175], v[36:39]
	v_mfma_f32_16x16x32_bf16 v[28:31], v[156:159], v[172:175], v[28:31]
	v_mfma_f32_16x16x32_bf16 v[20:23], v[148:151], v[180:183], v[20:23]
	v_mfma_f32_16x16x32_bf16 v[12:15], v[156:159], v[180:183], v[12:15]
	v_mfma_f32_16x16x32_bf16 v[4:7], v[148:151], v[188:191], v[4:7]
	v_mfma_f32_16x16x32_bf16 v[0:3], v[156:159], v[188:191], v[0:3]
	s_barrier
; #define PG8_STAGE(bufoff, gbase, voff) do { _Pragma("unroll") for (int _i = 0; _i < 2; ++_i) \
;         __builtin_amdgcn_global_load_lds((const unsigned*)((const char*)(gbase) + (voff)[_i]), (PG8_LAS unsigned*)(lds + (bufoff) + ldsw + _i * 8192), 16, 0, 0); } while (0)
; #define PG8_LDA(dst, b, h) do { _Pragma("unroll") for (int m = 0; m < 4; ++m) _Pragma("unroll") for (int k = 0; k < 2; ++k) dst[m][k] = *(const PG8_LAS bf16x8*)(lds + PG8_SA(b, h) + aoff + m * 2048 + k * 1024); } while (0)
; #define PG8_LDB(dst, b, h) do { _Pragma("unroll") for (int n = 0; n < 2; ++n) _Pragma("unroll") for (int k = 0; k < 2; ++k) dst[n][k] = *(const PG8_LAS bf16x8*)(lds + PG8_SB(b, h) + boff + n * 2048 + k * 1024); } while (0)
; #define PG8_MMA(ai, bj, At, Bt) do { __builtin_amdgcn_s_setprio(1); _Pragma("unroll") for (int m = 0; m < 4; ++m) _Pragma("unroll") for (int n = 0; n < 2; ++n) _Pragma("unroll") for (int k = 0; k < 2; ++k) \
;         acc[ai][bj][m][n] = __builtin_amdgcn_mfma_f32_16x16x32_bf16(Bt[n][k], At[m][k], acc[ai][bj][m][n], 0, 0, 0); __builtin_amdgcn_s_setprio(0); } while (0)
; #define PG8_WAIT_V(n) asm volatile("s_waitcnt vmcnt(" #n ")" ::: "memory")
; #define PG8_WAIT_L(n) asm volatile("s_waitcnt lgkmcnt(" #n ")" ::: "memory")
; #define PG8_BAR __builtin_amdgcn_s_barrier()
; #define PG8_SCHED __builtin_amdgcn_sched_barrier(0)
; template <class Epi, class Sched, bool ALIGN_EPI = false, bool SP2 = false>
; __device__ __forceinline__ void gemm_phase(PG8_LAS unsigned char* lds, const Gemm g, const Sched& S, const Epi& E) {
;     ...
;             PG8_LDB(B0, 1, 0); PG8_LDB(B1, 1, 1); PG8_SCHED; PG8_LDA(At, 1, 0); PG8_STAGE(PG8_SA(0, 1), a2 + hstepA, voffA);
;             PG8_WAIT_V(8); PG8_WAIT_L(0); PG8_BAR; PG8_MMA(0, 0, At, B0); PG8_MMA(0, 1, At, B1); PG8_BAR; PG8_SCHED;
;             PG8_LDA(At, 1, 1); PG8_STAGE(PG8_SB(1, 0), b3, voffB); PG8_STAGE(PG8_SB(1, 1), b3 + hstepB, voffB); PG8_STAGE(PG8_SA(1, 0), a3, voffA);
;             PG8_WAIT_V(8); PG8_WAIT_L(0); PG8_BAR; PG8_MMA(1, 0, At, B0); PG8_MMA(1, 1, At, B1); PG8_BAR; PG8_SCHED;
	s_add_i32 s3, 0, 0x18000
	s_add_i32 s30, 0, 0x1c000
	v_add_u32_e32 v140, s3, v222
	v_add_u32_e32 v156, s30, v222
	ds_read_b128 v[128:131], v140
	ds_read_b128 v[132:135], v140 offset:1024
	ds_read_b128 v[136:139], v140 offset:2048
	ds_read_b128 v[140:143], v140 offset:3072
	ds_read_b128 v[144:147], v156
	ds_read_b128 v[148:151], v156 offset:1024
	ds_read_b128 v[152:155], v156 offset:2048
	ds_read_b128 v[156:159], v156 offset:3072
	s_add_u32 s66, s82, 0x130000
	s_addc_u32 s67, s83, 0
	s_mov_b32 m0, s64
	ds_read_b128 v[160:163], v223 offset:32768
	ds_read_b128 v[164:167], v223 offset:33792
	ds_read_b128 v[168:171], v223 offset:34816
	ds_read_b128 v[172:175], v223 offset:35840
	ds_read_b128 v[176:179], v223 offset:36864
	ds_read_b128 v[180:183], v223 offset:37888
	ds_read_b128 v[184:187], v223 offset:38912
	ds_read_b128 v[188:191], v223 offset:39936
	global_load_lds_dwordx4 v202, s[66:67]
	s_mov_b32 m0, s65
	s_nop 0
	global_load_lds_dwordx4 v200, s[66:67]
	s_waitcnt vmcnt(8)
	s_waitcnt lgkmcnt(0)
	s_barrier
	s_waitcnt lgkmcnt(0)
	v_mfma_f32_16x16x32_bf16 v[124:127], v[128:131], v[160:163], v[124:127]
	v_mfma_f32_16x16x32_bf16 v[120:123], v[136:139], v[160:163], v[120:123]
	v_mfma_f32_16x16x32_bf16 v[112:115], v[128:131], v[168:171], v[112:115]
	v_mfma_f32_16x16x32_bf16 v[104:107], v[136:139], v[168:171], v[104:107]
	v_mfma_f32_16x16x32_bf16 v[96:99], v[128:131], v[176:179], v[96:99]
	v_mfma_f32_16x16x32_bf16 v[88:91], v[136:139], v[176:179], v[88:91]
	v_mfma_f32_16x16x32_bf16 v[80:83], v[128:131], v[184:187], v[80:83]
	v_mfma_f32_16x16x32_bf16 v[72:75], v[136:139], v[184:187], v[72:75]
	v_mfma_f32_16x16x32_bf16 v[124:127], v[132:135], v[164:167], v[124:127]
	v_mfma_f32_16x16x32_bf16 v[120:123], v[140:143], v[164:167], v[120:123]
	v_mfma_f32_16x16x32_bf16 v[112:115], v[132:135], v[172:175], v[112:115]
	v_mfma_f32_16x16x32_bf16 v[104:107], v[140:143], v[172:175], v[104:107]
	v_mfma_f32_16x16x32_bf16 v[96:99], v[132:135], v[180:183], v[96:99]
	v_mfma_f32_16x16x32_bf16 v[88:91], v[140:143], v[180:183], v[88:91]
	v_mfma_f32_16x16x32_bf16 v[80:83], v[132:135], v[188:191], v[80:83]
	v_mfma_f32_16x16x32_bf16 v[72:75], v[140:143], v[188:191], v[72:75]
	v_mfma_f32_16x16x32_bf16 v[116:119], v[144:147], v[160:163], v[116:119]
	v_mfma_f32_16x16x32_bf16 v[108:111], v[152:155], v[160:163], v[108:111]
	v_mfma_f32_16x16x32_bf16 v[100:103], v[144:147], v[168:171], v[100:103]
	v_mfma_f32_16x16x32_bf16 v[92:95], v[152:155], v[168:171], v[92:95]
	v_mfma_f32_16x16x32_bf16 v[84:87], v[144:147], v[176:179], v[84:87]
	v_mfma_f32_16x16x32_bf16 v[76:79], v[152:155], v[176:179], v[76:79]
	v_mfma_f32_16x16x32_bf16 v[68:71], v[144:147], v[184:187], v[68:71]
	v_mfma_f32_16x16x32_bf16 v[64:67], v[152:155], v[184:187], v[64:67]
	v_mfma_f32_16x16x32_bf16 v[116:119], v[148:151], v[164:167], v[116:119]
	v_mfma_f32_16x16x32_bf16 v[108:111], v[156:159], v[164:167], v[108:111]
	v_mfma_f32_16x16x32_bf16 v[100:103], v[148:151], v[172:175], v[100:103]
	v_mfma_f32_16x16x32_bf16 v[92:95], v[156:159], v[172:175], v[92:95]
	v_mfma_f32_16x16x32_bf16 v[84:87], v[148:151], v[180:183], v[84:87]
	v_mfma_f32_16x16x32_bf16 v[76:79], v[156:159], v[180:183], v[76:79]
	v_mfma_f32_16x16x32_bf16 v[68:71], v[148:151], v[188:191], v[68:71]
	v_mfma_f32_16x16x32_bf16 v[64:67], v[156:159], v[188:191], v[64:67]
	s_barrier
	s_add_i32 s3, s3, s49
	s_add_i32 m0, s3, 0xffffff80
	ds_read_b128 v[160:163], v223 offset:49152
	ds_read_b128 v[164:167], v223 offset:50176
	ds_read_b128 v[168:171], v223 offset:51200
	ds_read_b128 v[172:175], v223 offset:52224
	ds_read_b128 v[176:179], v223 offset:53248
	ds_read_b128 v[180:183], v223 offset:54272
	ds_read_b128 v[184:187], v223 offset:55296
	ds_read_b128 v[188:191], v223 offset:56320
	global_load_lds_dwordx4 v192, s[96:97] offset:128
	s_add_i32 m0, s3, 0x1f80
	s_add_i32 s3, s30, s49
	global_load_lds_dwordx4 v198, s[96:97] offset:128
	v_lshl_add_u64 v[208:209], v[212:213], 0, s[36:37]
	s_mov_b32 m0, s3
	s_nop 0
	global_load_lds_dwordx4 v[208:209], off
	v_lshl_add_u64 v[208:209], v[214:215], 0, s[36:37]
	s_add_i32 m0, s3, 0x2000
	s_nop 0
	global_load_lds_dwordx4 v[208:209], off
	s_add_i32 m0, s86, 0xffffff80
	s_nop 0
	global_load_lds_dwordx4 v202, s[82:83] offset:128
	s_add_i32 m0, s87, 0xffffff80
	s_nop 0
	global_load_lds_dwordx4 v200, s[82:83] offset:128
	s_waitcnt vmcnt(8)
	s_waitcnt lgkmcnt(0)
	s_barrier
	s_waitcnt lgkmcnt(0)
	v_mfma_f32_16x16x32_bf16 v[60:63], v[128:131], v[160:163], v[60:63]
	v_mfma_f32_16x16x32_bf16 v[56:59], v[136:139], v[160:163], v[56:59]
	v_mfma_f32_16x16x32_bf16 v[48:51], v[128:131], v[168:171], v[48:51]
	v_mfma_f32_16x16x32_bf16 v[40:43], v[136:139], v[168:171], v[40:43]
	v_mfma_f32_16x16x32_bf16 v[32:35], v[128:131], v[176:179], v[32:35]
	v_mfma_f32_16x16x32_bf16 v[24:27], v[136:139], v[176:179], v[24:27]
	v_mfma_f32_16x16x32_bf16 v[16:19], v[128:131], v[184:187], v[16:19]
	v_mfma_f32_16x16x32_bf16 v[8:11], v[136:139], v[184:187], v[8:11]
	v_mfma_f32_16x16x32_bf16 v[60:63], v[132:135], v[164:167], v[60:63]
	v_mfma_f32_16x16x32_bf16 v[56:59], v[140:143], v[164:167], v[56:59]
	v_mfma_f32_16x16x32_bf16 v[48:51], v[132:135], v[172:175], v[48:51]
	v_mfma_f32_16x16x32_bf16 v[40:43], v[140:143], v[172:175], v[40:43]
	v_mfma_f32_16x16x32_bf16 v[32:35], v[132:135], v[180:183], v[32:35]
	v_mfma_f32_16x16x32_bf16 v[24:27], v[140:143], v[180:183], v[24:27]
	v_mfma_f32_16x16x32_bf16 v[16:19], v[132:135], v[188:191], v[16:19]
	v_mfma_f32_16x16x32_bf16 v[8:11], v[140:143], v[188:191], v[8:11]
	v_mfma_f32_16x16x32_bf16 v[52:55], v[144:147], v[160:163], v[52:55]
	v_mfma_f32_16x16x32_bf16 v[44:47], v[152:155], v[160:163], v[44:47]
	v_mfma_f32_16x16x32_bf16 v[36:39], v[144:147], v[168:171], v[36:39]
	v_mfma_f32_16x16x32_bf16 v[28:31], v[152:155], v[168:171], v[28:31]
	v_mfma_f32_16x16x32_bf16 v[20:23], v[144:147], v[176:179], v[20:23]
	v_mfma_f32_16x16x32_bf16 v[12:15], v[152:155], v[176:179], v[12:15]
	v_mfma_f32_16x16x32_bf16 v[4:7], v[144:147], v[184:187], v[4:7]
	v_mfma_f32_16x16x32_bf16 v[0:3], v[152:155], v[184:187], v[0:3]
	v_mfma_f32_16x16x32_bf16 v[52:55], v[148:151], v[164:167], v[52:55]
	v_mfma_f32_16x16x32_bf16 v[44:47], v[156:159], v[164:167], v[44:47]
	v_mfma_f32_16x16x32_bf16 v[36:39], v[148:151], v[172:175], v[36:39]
	v_mfma_f32_16x16x32_bf16 v[28:31], v[156:159], v[172:175], v[28:31]
	v_mfma_f32_16x16x32_bf16 v[20:23], v[148:151], v[180:183], v[20:23]
	v_mfma_f32_16x16x32_bf16 v[12:15], v[156:159], v[180:183], v[12:15]
	v_mfma_f32_16x16x32_bf16 v[4:7], v[148:151], v[188:191], v[4:7]
	v_mfma_f32_16x16x32_bf16 v[0:3], v[156:159], v[188:191], v[0:3]
	s_barrier
	s_add_u32 s93, s93, 0x100
	s_addc_u32 s94, s94, 0
	s_cmp_ge_u32 s2, s80
	s_mov_b64 s[66:67], s[4:5]
	s_mov_b32 s82, s2
	s_cbranch_scc0 .LBB0_766
	s_and_b64 vcc, exec, s[12:13]
	s_cbranch_vccz .LBB0_769
	s_barrier

; #define PG8_STAGE(bufoff, gbase, voff) do { _Pragma("unroll") for (int _i = 0; _i < 2; ++_i) \
;         __builtin_amdgcn_global_load_lds((const unsigned*)((const char*)(gbase) + (voff)[_i]), (PG8_LAS unsigned*)(lds + (bufoff) + ldsw + _i * 8192), 16, 0, 0); } while (0)
; #define PG8_LDA(dst, b, h) do { _Pragma("unroll") for (int m = 0; m < 4; ++m) _Pragma("unroll") for (int k = 0; k < 2; ++k) dst[m][k] = *(const PG8_LAS bf16x8*)(lds + PG8_SA(b, h) + aoff + m * 2048 + k * 1024); } while (0)
; #define PG8_LDB(dst, b, h) do { _Pragma("unroll") for (int n = 0; n < 2; ++n) _Pragma("unroll") for (int k = 0; k < 2; ++k) dst[n][k] = *(const PG8_LAS bf16x8*)(lds + PG8_SB(b, h) + boff + n * 2048 + k * 1024); } while (0)
; #define PG8_MMA(ai, bj, At, Bt) do { __builtin_amdgcn_s_setprio(1); _Pragma("unroll") for (int m = 0; m < 4; ++m) _Pragma("unroll") for (int n = 0; n < 2; ++n) _Pragma("unroll") for (int k = 0; k < 2; ++k) \
;         acc[ai][bj][m][n] = __builtin_amdgcn_mfma_f32_16x16x32_bf16(Bt[n][k], At[m][k], acc[ai][bj][m][n], 0, 0, 0); __builtin_amdgcn_s_setprio(0); } while (0)
; #define PG8_WAIT_V(n) asm volatile("s_waitcnt vmcnt(" #n ")" ::: "memory")
; #define PG8_WAIT_L(n) asm volatile("s_waitcnt lgkmcnt(" #n ")" ::: "memory")
; #define PG8_BAR __builtin_amdgcn_s_barrier()
; template <class Epi, class Sched, bool ALIGN_EPI = false, bool SP2 = false>
; __device__ __forceinline__ void gemm_phase(PG8_LAS unsigned char* lds, const Gemm g, const Sched& S, const Epi& E) {
;     ...
;             const char* a1 = cA + (size_t)(t + 1) * kstep;
;             const char* a2 = last ? nA : cA + (size_t)(t + 2) * kstep; const char* b2 = last ? nB : cB + (size_t)(t + 2) * kstep;
;             const char* a3 = a2 + kstep; const char* b3 = b2 + kstep;
;             if (last && has_next) S.a_ready(nxt);
;             if constexpr (SP2) {
;             PG8_LDB(B0, 0, 0); PG8_LDB(B1, 0, 1); PG8_SCHED; PG8_LDA(At, 0, 0); PG8_STAGE(PG8_SA(1, 1), a1 + hstepA, voffA);
;             PG8_WAIT_V(8); PG8_WAIT_L(0); PG8_BAR; PG8_MMA(0, 0, At, B0); PG8_MMA(0, 1, At, B1); PG8_BAR; PG8_SCHED;
;             PG8_LDA(At, 0, 1); PG8_STAGE(PG8_SB(0, 0), b2, voffB); PG8_STAGE(PG8_SB(0, 1), b2 + hstepB, voffB); PG8_STAGE(PG8_SA(0, 0), a2, voffA);
;             PG8_WAIT_V(8); PG8_WAIT_L(0); PG8_BAR; PG8_MMA(1, 0, At, B0); PG8_MMA(1, 1, At, B1); PG8_BAR; PG8_SCHED;
.LBB0_817:
	s_add_u32 s2, s0, 0xfffc0080
	s_addc_u32 s3, s1, -1
	s_add_i32 s30, 0, 0x10000
	s_cmp_eq_u32 s78, 12
	s_cselect_b32 s11, s7, s3
	s_cselect_b32 s10, s12, s2
	s_cselect_b32 s9, s13, s17
	s_cselect_b32 s8, s15, s16
	s_add_i32 s31, 0, 0x14000
	v_add_u32_e32 v84, s30, v240
	v_add_u32_e32 v116, s31, v240
	ds_read_b128 v[72:75], v84
	ds_read_b128 v[76:79], v84 offset:1024
	ds_read_b128 v[80:83], v84 offset:2048
	ds_read_b128 v[84:87], v84 offset:3072
	ds_read_b128 v[104:107], v116
	ds_read_b128 v[108:111], v116 offset:1024
	ds_read_b128 v[112:115], v116 offset:2048
	ds_read_b128 v[116:119], v116 offset:3072
	s_add_i32 m0, s19, 0xc000
	ds_read_b128 v[136:139], v241
	ds_read_b128 v[140:143], v241 offset:1024
	ds_read_b128 v[144:147], v241 offset:2048
	ds_read_b128 v[148:151], v241 offset:3072
	ds_read_b128 v[168:171], v241 offset:4096
	ds_read_b128 v[172:175], v241 offset:5120
	ds_read_b128 v[176:179], v241 offset:6144
	ds_read_b128 v[180:183], v241 offset:7168
	global_load_lds_dwordx4 v206, s[0:1]
	s_add_i32 m0, s19, 0xe000
	s_nop 0
	global_load_lds_dwordx4 v204, s[0:1]
	s_waitcnt vmcnt(8)
	s_waitcnt lgkmcnt(0)
	s_barrier
	s_waitcnt lgkmcnt(0)
	v_mfma_f32_16x16x32_bf16 v[188:191], v[72:75], v[136:139], v[188:191]
	v_mfma_f32_16x16x32_bf16 v[184:187], v[80:83], v[136:139], v[184:187]
	v_mfma_f32_16x16x32_bf16 v[156:159], v[72:75], v[144:147], v[156:159]
	v_mfma_f32_16x16x32_bf16 v[152:155], v[80:83], v[144:147], v[152:155]
	v_mfma_f32_16x16x32_bf16 v[124:127], v[72:75], v[168:171], v[124:127]
	v_mfma_f32_16x16x32_bf16 v[120:123], v[80:83], v[168:171], v[120:123]
	v_mfma_f32_16x16x32_bf16 v[92:95], v[72:75], v[176:179], v[92:95]
	v_mfma_f32_16x16x32_bf16 v[88:91], v[80:83], v[176:179], v[88:91]
	v_mfma_f32_16x16x32_bf16 v[188:191], v[76:79], v[140:143], v[188:191]
	v_mfma_f32_16x16x32_bf16 v[184:187], v[84:87], v[140:143], v[184:187]
	v_mfma_f32_16x16x32_bf16 v[156:159], v[76:79], v[148:151], v[156:159]
	v_mfma_f32_16x16x32_bf16 v[152:155], v[84:87], v[148:151], v[152:155]
	v_mfma_f32_16x16x32_bf16 v[124:127], v[76:79], v[172:175], v[124:127]
	v_mfma_f32_16x16x32_bf16 v[120:123], v[84:87], v[172:175], v[120:123]
	v_mfma_f32_16x16x32_bf16 v[92:95], v[76:79], v[180:183], v[92:95]
	v_mfma_f32_16x16x32_bf16 v[88:91], v[84:87], v[180:183], v[88:91]
	v_mfma_f32_16x16x32_bf16 v[164:167], v[104:107], v[136:139], v[164:167]
	v_mfma_f32_16x16x32_bf16 v[132:135], v[104:107], v[144:147], v[132:135]
	v_mfma_f32_16x16x32_bf16 v[128:131], v[112:115], v[144:147], v[128:131]
	v_mfma_f32_16x16x32_bf16 v[100:103], v[104:107], v[168:171], v[100:103]
	v_mfma_f32_16x16x32_bf16 v[96:99], v[112:115], v[168:171], v[96:99]
	v_mfma_f32_16x16x32_bf16 v[68:71], v[104:107], v[176:179], v[68:71]
	v_mfma_f32_16x16x32_bf16 v[64:67], v[112:115], v[176:179], v[64:67]
	v_mfma_f32_16x16x32_bf16 v[164:167], v[108:111], v[140:143], v[164:167]
	v_mfma_f32_16x16x32_bf16 v[136:139], v[112:115], v[136:139], v[160:163]
	v_mfma_f32_16x16x32_bf16 v[132:135], v[108:111], v[148:151], v[132:135]
	v_mfma_f32_16x16x32_bf16 v[128:131], v[116:119], v[148:151], v[128:131]
	v_mfma_f32_16x16x32_bf16 v[100:103], v[108:111], v[172:175], v[100:103]
	v_mfma_f32_16x16x32_bf16 v[96:99], v[116:119], v[172:175], v[96:99]
	v_mfma_f32_16x16x32_bf16 v[68:71], v[108:111], v[180:183], v[68:71]
	v_mfma_f32_16x16x32_bf16 v[64:67], v[116:119], v[180:183], v[64:67]
	v_mfma_f32_16x16x32_bf16 v[136:139], v[116:119], v[140:143], v[136:139]
	s_barrier
	s_add_i32 s2, s30, s18
	s_mov_b32 m0, s2
	ds_read_b128 v[140:143], v241 offset:16384
	ds_read_b128 v[144:147], v241 offset:17408
	ds_read_b128 v[148:151], v241 offset:18432
	ds_read_b128 v[160:163], v241 offset:19456
	ds_read_b128 v[168:171], v241 offset:20480
	ds_read_b128 v[172:175], v241 offset:21504
	ds_read_b128 v[176:179], v241 offset:22528
	ds_read_b128 v[180:183], v241 offset:23552
	global_load_lds_dwordx4 v192, s[8:9]
	s_add_i32 m0, s2, 0x2000
	s_add_u32 s2, s8, 0x40000
	s_addc_u32 s3, s9, 0
	s_add_i32 s30, s31, s18
	global_load_lds_dwordx4 v202, s[8:9]
	s_mov_b32 m0, s30
	s_nop 0
	global_load_lds_dwordx4 v192, s[2:3]
	s_add_i32 m0, s30, 0x2000
	s_nop 0
	global_load_lds_dwordx4 v202, s[2:3]
	s_mov_b32 m0, s19
	s_nop 0
	global_load_lds_dwordx4 v198, s[10:11]
	s_mov_b32 m0, s45
	s_nop 0
	global_load_lds_dwordx4 v200, s[10:11]
	s_waitcnt vmcnt(8)
	s_waitcnt lgkmcnt(0)
	s_barrier
	s_waitcnt lgkmcnt(0)
	v_mfma_f32_16x16x32_bf16 v[60:63], v[72:75], v[140:143], v[60:63]
	v_mfma_f32_16x16x32_bf16 v[56:59], v[80:83], v[140:143], v[56:59]
	v_mfma_f32_16x16x32_bf16 v[44:47], v[72:75], v[148:151], v[44:47]
	v_mfma_f32_16x16x32_bf16 v[40:43], v[80:83], v[148:151], v[40:43]
	v_mfma_f32_16x16x32_bf16 v[28:31], v[72:75], v[168:171], v[28:31]
	v_mfma_f32_16x16x32_bf16 v[24:27], v[80:83], v[168:171], v[24:27]
	v_mfma_f32_16x16x32_bf16 v[12:15], v[72:75], v[176:179], v[12:15]
	v_mfma_f32_16x16x32_bf16 v[8:11], v[80:83], v[176:179], v[8:11]
	v_mfma_f32_16x16x32_bf16 v[60:63], v[76:79], v[144:147], v[60:63]
	v_mfma_f32_16x16x32_bf16 v[56:59], v[84:87], v[144:147], v[56:59]
	v_mfma_f32_16x16x32_bf16 v[44:47], v[76:79], v[160:163], v[44:47]
	v_mfma_f32_16x16x32_bf16 v[40:43], v[84:87], v[160:163], v[40:43]
	v_mfma_f32_16x16x32_bf16 v[28:31], v[76:79], v[172:175], v[28:31]
	v_mfma_f32_16x16x32_bf16 v[24:27], v[84:87], v[172:175], v[24:27]
	v_mfma_f32_16x16x32_bf16 v[12:15], v[76:79], v[180:183], v[12:15]
	v_mfma_f32_16x16x32_bf16 v[8:11], v[84:87], v[180:183], v[8:11]
	v_mfma_f32_16x16x32_bf16 v[52:55], v[104:107], v[140:143], v[52:55]
	v_mfma_f32_16x16x32_bf16 v[48:51], v[112:115], v[140:143], v[48:51]
	v_mfma_f32_16x16x32_bf16 v[36:39], v[104:107], v[148:151], v[36:39]
	v_mfma_f32_16x16x32_bf16 v[32:35], v[112:115], v[148:151], v[32:35]
	v_mfma_f32_16x16x32_bf16 v[20:23], v[104:107], v[168:171], v[20:23]
	v_mfma_f32_16x16x32_bf16 v[16:19], v[112:115], v[168:171], v[16:19]
	v_mfma_f32_16x16x32_bf16 v[4:7], v[104:107], v[176:179], v[4:7]
	v_mfma_f32_16x16x32_bf16 v[0:3], v[112:115], v[176:179], v[0:3]
	v_mfma_f32_16x16x32_bf16 v[52:55], v[108:111], v[144:147], v[52:55]
	v_mfma_f32_16x16x32_bf16 v[48:51], v[116:119], v[144:147], v[48:51]
	v_mfma_f32_16x16x32_bf16 v[36:39], v[108:111], v[160:163], v[36:39]
	v_mfma_f32_16x16x32_bf16 v[32:35], v[116:119], v[160:163], v[32:35]
	v_mfma_f32_16x16x32_bf16 v[20:23], v[108:111], v[172:175], v[20:23]
	v_mfma_f32_16x16x32_bf16 v[16:19], v[116:119], v[172:175], v[16:19]
	v_mfma_f32_16x16x32_bf16 v[4:7], v[108:111], v[180:183], v[4:7]
	v_mfma_f32_16x16x32_bf16 v[0:3], v[116:119], v[180:183], v[0:3]
	s_barrier
; #define PG8_STAGE(bufoff, gbase, voff) do { _Pragma("unroll") for (int _i = 0; _i < 2; ++_i) \
;         __builtin_amdgcn_global_load_lds((const unsigned*)((const char*)(gbase) + (voff)[_i]), (PG8_LAS unsigned*)(lds + (bufoff) + ldsw + _i * 8192), 16, 0, 0); } while (0)
; #define PG8_LDA(dst, b, h) do { _Pragma("unroll") for (int m = 0; m < 4; ++m) _Pragma("unroll") for (int k = 0; k < 2; ++k) dst[m][k] = *(const PG8_LAS bf16x8*)(lds + PG8_SA(b, h) + aoff + m * 2048 + k * 1024); } while (0)
; #define PG8_LDB(dst, b, h) do { _Pragma("unroll") for (int n = 0; n < 2; ++n) _Pragma("unroll") for (int k = 0; k < 2; ++k) dst[n][k] = *(const PG8_LAS bf16x8*)(lds + PG8_SB(b, h) + boff + n * 2048 + k * 1024); } while (0)
; #define PG8_MMA(ai, bj, At, Bt) do { __builtin_amdgcn_s_setprio(1); _Pragma("unroll") for (int m = 0; m < 4; ++m) _Pragma("unroll") for (int n = 0; n < 2; ++n) _Pragma("unroll") for (int k = 0; k < 2; ++k) \
;         acc[ai][bj][m][n] = __builtin_amdgcn_mfma_f32_16x16x32_bf16(Bt[n][k], At[m][k], acc[ai][bj][m][n], 0, 0, 0); __builtin_amdgcn_s_setprio(0); } while (0)
; #define PG8_WAIT_V(n) asm volatile("s_waitcnt vmcnt(" #n ")" ::: "memory")
; #define PG8_WAIT_L(n) asm volatile("s_waitcnt lgkmcnt(" #n ")" ::: "memory")
; #define PG8_BAR __builtin_amdgcn_s_barrier()
; #define PG8_SCHED __builtin_amdgcn_sched_barrier(0)
; template <class Epi, class Sched, bool ALIGN_EPI = false, bool SP2 = false>
; __device__ __forceinline__ void gemm_phase(PG8_LAS unsigned char* lds, const Gemm g, const Sched& S, const Epi& E) {
;     ...
;             PG8_LDB(B0, 1, 0); PG8_LDB(B1, 1, 1); PG8_SCHED; PG8_LDA(At, 1, 0); PG8_STAGE(PG8_SA(0, 1), a2 + hstepA, voffA);
;             PG8_WAIT_V(8); PG8_WAIT_L(0); PG8_BAR; PG8_MMA(0, 0, At, B0); PG8_MMA(0, 1, At, B1); PG8_BAR; PG8_SCHED;
;             PG8_LDA(At, 1, 1); PG8_STAGE(PG8_SB(1, 0), b3, voffB); PG8_STAGE(PG8_SB(1, 1), b3 + hstepB, voffB); PG8_STAGE(PG8_SA(1, 0), a3, voffA);
;             PG8_WAIT_V(8); PG8_WAIT_L(0); PG8_BAR; PG8_MMA(1, 0, At, B0); PG8_MMA(1, 1, At, B1); PG8_BAR; PG8_SCHED;
	s_add_i32 s30, 0, 0x18000
	s_add_i32 s31, 0, 0x1c000
	v_add_u32_e32 v84, s30, v240
	v_add_u32_e32 v116, s31, v240
	ds_read_b128 v[72:75], v84
	ds_read_b128 v[76:79], v84 offset:1024
	ds_read_b128 v[80:83], v84 offset:2048
	ds_read_b128 v[84:87], v84 offset:3072
	ds_read_b128 v[104:107], v116
	ds_read_b128 v[108:111], v116 offset:1024
	ds_read_b128 v[112:115], v116 offset:2048
	ds_read_b128 v[116:119], v116 offset:3072
	s_add_u32 s2, s10, 0x40000
	s_addc_u32 s3, s11, 0
	s_mov_b32 m0, s64
	ds_read_b128 v[140:143], v241 offset:32768
	ds_read_b128 v[144:147], v241 offset:33792
	ds_read_b128 v[148:151], v241 offset:34816
	ds_read_b128 v[168:171], v241 offset:35840
	ds_read_b128 v[172:175], v241 offset:36864
	ds_read_b128 v[176:179], v241 offset:37888
	ds_read_b128 v[180:183], v241 offset:38912
	ds_read_b128 v[208:211], v241 offset:39936
	global_load_lds_dwordx4 v198, s[2:3]
	s_mov_b32 m0, s65
	s_nop 0
	global_load_lds_dwordx4 v200, s[2:3]
	s_waitcnt vmcnt(8)
	s_waitcnt lgkmcnt(0)
	s_barrier
	s_waitcnt lgkmcnt(0)
	v_mfma_f32_16x16x32_bf16 v[160:163], v[72:75], v[140:143], v[188:191]
	v_mfma_f32_16x16x32_bf16 v[188:191], v[76:79], v[144:147], v[160:163]
	v_mfma_f32_16x16x32_bf16 v[160:163], v[80:83], v[140:143], v[184:187]
	v_mfma_f32_16x16x32_bf16 v[156:159], v[72:75], v[148:151], v[156:159]
	v_mfma_f32_16x16x32_bf16 v[152:155], v[80:83], v[148:151], v[152:155]
	v_mfma_f32_16x16x32_bf16 v[124:127], v[72:75], v[172:175], v[124:127]
	v_mfma_f32_16x16x32_bf16 v[120:123], v[80:83], v[172:175], v[120:123]
	v_mfma_f32_16x16x32_bf16 v[92:95], v[72:75], v[180:183], v[92:95]
	v_mfma_f32_16x16x32_bf16 v[88:91], v[80:83], v[180:183], v[88:91]
	v_mfma_f32_16x16x32_bf16 v[184:187], v[84:87], v[144:147], v[160:163]
	v_mfma_f32_16x16x32_bf16 v[156:159], v[76:79], v[168:171], v[156:159]
	v_mfma_f32_16x16x32_bf16 v[152:155], v[84:87], v[168:171], v[152:155]
	v_mfma_f32_16x16x32_bf16 v[124:127], v[76:79], v[176:179], v[124:127]
	v_mfma_f32_16x16x32_bf16 v[120:123], v[84:87], v[176:179], v[120:123]
	v_mfma_f32_16x16x32_bf16 v[92:95], v[76:79], v[208:211], v[92:95]
	v_mfma_f32_16x16x32_bf16 v[88:91], v[84:87], v[208:211], v[88:91]
	v_mfma_f32_16x16x32_bf16 v[160:163], v[104:107], v[140:143], v[164:167]
	v_mfma_f32_16x16x32_bf16 v[136:139], v[112:115], v[140:143], v[136:139]
	v_mfma_f32_16x16x32_bf16 v[132:135], v[104:107], v[148:151], v[132:135]
	v_mfma_f32_16x16x32_bf16 v[128:131], v[112:115], v[148:151], v[128:131]
	v_mfma_f32_16x16x32_bf16 v[100:103], v[104:107], v[172:175], v[100:103]
	v_mfma_f32_16x16x32_bf16 v[96:99], v[112:115], v[172:175], v[96:99]
	v_mfma_f32_16x16x32_bf16 v[68:71], v[104:107], v[180:183], v[68:71]
	v_mfma_f32_16x16x32_bf16 v[64:67], v[112:115], v[180:183], v[64:67]
	v_mfma_f32_16x16x32_bf16 v[164:167], v[108:111], v[144:147], v[160:163]
	v_mfma_f32_16x16x32_bf16 v[160:163], v[116:119], v[144:147], v[136:139]
	v_mfma_f32_16x16x32_bf16 v[132:135], v[108:111], v[168:171], v[132:135]
	v_mfma_f32_16x16x32_bf16 v[128:131], v[116:119], v[168:171], v[128:131]
	v_mfma_f32_16x16x32_bf16 v[100:103], v[108:111], v[176:179], v[100:103]
	v_mfma_f32_16x16x32_bf16 v[96:99], v[116:119], v[176:179], v[96:99]
	v_mfma_f32_16x16x32_bf16 v[68:71], v[108:111], v[208:211], v[68:71]
	v_mfma_f32_16x16x32_bf16 v[64:67], v[116:119], v[208:211], v[64:67]
	s_barrier
	s_add_i32 s2, s30, s18
	s_add_i32 m0, s2, 0xffffff80
	ds_read_b128 v[136:139], v241 offset:49152
	ds_read_b128 v[140:143], v241 offset:50176
	ds_read_b128 v[144:147], v241 offset:51200
	ds_read_b128 v[148:151], v241 offset:52224
	ds_read_b128 v[168:171], v241 offset:53248
	ds_read_b128 v[172:175], v241 offset:54272
	ds_read_b128 v[176:179], v241 offset:55296
	ds_read_b128 v[180:183], v241 offset:56320
	global_load_lds_dwordx4 v192, s[8:9] offset:128
	s_add_i32 m0, s2, 0x1f80
	s_add_u32 s2, s8, 0x40080
	global_load_lds_dwordx4 v202, s[8:9] offset:128
	s_addc_u32 s3, s9, 0
	s_add_i32 s8, s31, s18
	s_mov_b32 m0, s8
	s_nop 0
	global_load_lds_dwordx4 v192, s[2:3]
	s_add_i32 m0, s8, 0x2000
	s_nop 0
	global_load_lds_dwordx4 v202, s[2:3]
	s_add_i32 m0, s21, 0xffffff80
	s_nop 0
	global_load_lds_dwordx4 v198, s[10:11] offset:128
	s_add_i32 m0, s62, 0xffffff80
	s_nop 0
	global_load_lds_dwordx4 v200, s[10:11] offset:128
	s_waitcnt vmcnt(8)
	s_waitcnt lgkmcnt(0)
	s_barrier
	s_waitcnt lgkmcnt(0)
	v_mfma_f32_16x16x32_bf16 v[60:63], v[72:75], v[136:139], v[60:63]
	v_mfma_f32_16x16x32_bf16 v[56:59], v[80:83], v[136:139], v[56:59]
	v_mfma_f32_16x16x32_bf16 v[44:47], v[72:75], v[144:147], v[44:47]
	v_mfma_f32_16x16x32_bf16 v[40:43], v[80:83], v[144:147], v[40:43]
	v_mfma_f32_16x16x32_bf16 v[28:31], v[72:75], v[168:171], v[28:31]
	v_mfma_f32_16x16x32_bf16 v[24:27], v[80:83], v[168:171], v[24:27]
	v_mfma_f32_16x16x32_bf16 v[12:15], v[72:75], v[176:179], v[12:15]
	v_mfma_f32_16x16x32_bf16 v[8:11], v[80:83], v[176:179], v[8:11]
	v_mfma_f32_16x16x32_bf16 v[60:63], v[76:79], v[140:143], v[60:63]
	v_mfma_f32_16x16x32_bf16 v[56:59], v[84:87], v[140:143], v[56:59]
	v_mfma_f32_16x16x32_bf16 v[44:47], v[76:79], v[148:151], v[44:47]
	v_mfma_f32_16x16x32_bf16 v[40:43], v[84:87], v[148:151], v[40:43]
	v_mfma_f32_16x16x32_bf16 v[28:31], v[76:79], v[172:175], v[28:31]
	v_mfma_f32_16x16x32_bf16 v[24:27], v[84:87], v[172:175], v[24:27]
	v_mfma_f32_16x16x32_bf16 v[12:15], v[76:79], v[180:183], v[12:15]
	v_mfma_f32_16x16x32_bf16 v[8:11], v[84:87], v[180:183], v[8:11]
	v_mfma_f32_16x16x32_bf16 v[52:55], v[104:107], v[136:139], v[52:55]
	v_mfma_f32_16x16x32_bf16 v[48:51], v[112:115], v[136:139], v[48:51]
	v_mfma_f32_16x16x32_bf16 v[36:39], v[104:107], v[144:147], v[36:39]
	v_mfma_f32_16x16x32_bf16 v[32:35], v[112:115], v[144:147], v[32:35]
	v_mfma_f32_16x16x32_bf16 v[20:23], v[104:107], v[168:171], v[20:23]
	v_mfma_f32_16x16x32_bf16 v[16:19], v[112:115], v[168:171], v[16:19]
	v_mfma_f32_16x16x32_bf16 v[4:7], v[104:107], v[176:179], v[4:7]
	v_mfma_f32_16x16x32_bf16 v[0:3], v[112:115], v[176:179], v[0:3]
	v_mfma_f32_16x16x32_bf16 v[52:55], v[108:111], v[140:143], v[52:55]
	v_mfma_f32_16x16x32_bf16 v[48:51], v[116:119], v[140:143], v[48:51]
	v_mfma_f32_16x16x32_bf16 v[36:39], v[108:111], v[148:151], v[36:39]
	v_mfma_f32_16x16x32_bf16 v[32:35], v[116:119], v[148:151], v[32:35]
	v_mfma_f32_16x16x32_bf16 v[20:23], v[108:111], v[172:175], v[20:23]
	v_mfma_f32_16x16x32_bf16 v[16:19], v[116:119], v[172:175], v[16:19]
	v_mfma_f32_16x16x32_bf16 v[4:7], v[108:111], v[180:183], v[4:7]
	v_mfma_f32_16x16x32_bf16 v[0:3], v[116:119], v[180:183], v[0:3]
	s_barrier
	s_add_i32 s78, s78, 2
	s_add_u32 s16, s16, 0x100
	s_addc_u32 s17, s17, 0
	s_add_u32 s0, s0, 0x100
	s_addc_u32 s1, s1, 0
	s_cmp_gt_u32 s78, 13
	s_cbranch_scc0 .LBB0_817
	s_and_b64 vcc, exec, s[66:67]
	s_cbranch_vccz .LBB0_820
	s_barrier
